# early barrier acquire + pipelined norm0 + batched sw_tasks reductions + mask-free fast path in windowed attention softmax
# speedup vs baseline: 1.0180x; 1.0180x over previous
.LBB0_196:
	s_or_b64 exec, exec, s[4:5]
	v_readlane_b32 s0, v253, 0
	v_readlane_b32 s1, v253, 1
	s_waitcnt lgkmcnt(0)
	s_barrier
	s_load_dwordx2 s[8:9], s[0:1], 0x160
	v_lshrrev_b32_e32 v147, 6, v146
	v_lshl_add_u32 v150, s69, 2, v147
	s_movk_i32 s0, 0x2000
	v_mbcnt_lo_u32_b32 v145, -1, 0
	s_waitcnt lgkmcnt(0)
	v_mov_b64_e32 v[80:81], s[8:9]
	v_cmp_gt_i32_e64 s[0:1], s0, v150
	s_mov_b64 s[6:7], exec
	s_nop 0
	v_writelane_b32 v253, s0, 12
	s_nop 1
	v_writelane_b32 v253, s1, 13
	s_and_b64 s[0:1], s[6:7], s[0:1]
	s_mov_b64 exec, s[0:1]
	s_cbranch_execz .LBB0_200
	v_readlane_b32 s10, v253, 0
	v_readlane_b32 s11, v253, 1
	s_load_dwordx2 s[4:5], s[10:11], 0x58
	s_load_dwordx4 s[12:15], s[10:11], 0x0
	s_load_dwordx2 s[0:1], s[10:11], 0x168
	v_mbcnt_hi_u32_b32 v0, -1, v145
	v_lshlrev_b32_e32 v1, 4, v0
	v_lshlrev_b32_e32 v3, 3, v0
	v_mov_b32_e32 v26, 0x358637bd
	v_xor_b32_e32 v2, 32, v0
	v_lshlrev_b32_e32 v16, 2, v2
	v_xor_b32_e32 v2, 16, v0
	v_lshlrev_b32_e32 v17, 2, v2
	v_xor_b32_e32 v2, 8, v0
	v_lshlrev_b32_e32 v18, 2, v2
	v_xor_b32_e32 v2, 4, v0
	v_lshlrev_b32_e32 v19, 2, v2
	v_xor_b32_e32 v2, 2, v0
	v_lshlrev_b32_e32 v20, 2, v2
	v_xor_b32_e32 v2, 1, v0
	v_lshlrev_b32_e32 v21, 2, v2
	s_add_u32 s2, s8, 0x2000000
	s_addc_u32 s3, s9, 0
	s_waitcnt lgkmcnt(0)
	s_mov_b64 s[16:17], s[4:5]
	s_add_u32 s4, s8, 0xf440000
	s_addc_u32 s5, s9, 0
	s_lshl_b32 s0, s0, 2
	v_readfirstlane_b32 s1, v150
	s_nop 3
	s_lshl_b32 s18, s1, 12
	s_cmp_lt_u32 s1, 0x1000
	s_cselect_b32 s10, s12, s14
	s_cselect_b32 s11, s13, s15
	s_cselect_b32 s19, 0, 0x1000000
	s_sub_u32 s18, s18, s19
	s_add_u32 s10, s10, s18
	s_addc_u32 s11, s11, 0
	global_load_dwordx4 v[32:35], v1, s[10:11]
	global_load_dwordx4 v[36:39], v1, s[10:11] offset:1024
	global_load_dwordx4 v[40:43], v1, s[10:11] offset:2048
	global_load_dwordx4 v[44:47], v1, s[10:11] offset:3072
	global_load_dwordx4 v[64:67], v1, s[16:17]
	global_load_dwordx4 v[68:71], v1, s[16:17] offset:1024
	global_load_dwordx4 v[72:75], v1, s[16:17] offset:2048
	global_load_dwordx4 v[76:79], v1, s[16:17] offset:3072
.Lnorm0_a:
	s_sub_i32 s16, s1, 0x1000
	s_ashr_i32 s16, s16, 10
	s_add_i32 s16, s16, 1
	s_cmp_lt_u32 s1, 0x1000
	s_cselect_b32 s16, 0, s16
	s_mul_i32 s16, s16, 0x3000
	s_add_u32 s16, s4, s16
	s_addc_u32 s17, s5, 0
	global_load_dwordx4 v[82:85], v1, s[16:17]
	global_load_dwordx4 v[86:89], v1, s[16:17] offset:1024
	global_load_dwordx4 v[90:93], v1, s[16:17] offset:2048
	global_load_dwordx4 v[94:97], v1, s[16:17] offset:3072
	s_add_u32 s16, s16, 0x1000
	s_addc_u32 s17, s17, 0
	global_load_dwordx4 v[98:101], v1, s[16:17]
	global_load_dwordx4 v[102:105], v1, s[16:17] offset:1024
	global_load_dwordx4 v[106:109], v1, s[16:17] offset:2048
	global_load_dwordx4 v[110:113], v1, s[16:17] offset:3072
	s_add_i32 s16, s1, s0
	s_cmp_lt_u32 s16, 0x2000
	s_cselect_b32 s17, s16, s1
	s_lshl_b32 s18, s17, 12
	s_cmp_lt_u32 s17, 0x1000
	s_cselect_b32 s10, s12, s14
	s_cselect_b32 s11, s13, s15
	s_cselect_b32 s19, 0, 0x1000000
	s_sub_u32 s18, s18, s19
	s_add_u32 s10, s10, s18
	s_addc_u32 s11, s11, 0
	global_load_dwordx4 v[48:51], v1, s[10:11]
	global_load_dwordx4 v[52:55], v1, s[10:11] offset:1024
	global_load_dwordx4 v[56:59], v1, s[10:11] offset:2048
	global_load_dwordx4 v[60:63], v1, s[10:11] offset:3072
	s_lshl_b32 s18, s1, 11
	s_add_u32 s18, s2, s18
	s_addc_u32 s19, s3, 0
	s_waitcnt vmcnt(16)
	v_pk_mul_f32 v[4:5], v[32:33], v[32:33]
	v_pk_mul_f32 v[6:7], v[34:35], v[34:35]
	v_pk_fma_f32 v[4:5], v[36:37], v[36:37], v[4:5]
	v_pk_fma_f32 v[6:7], v[38:39], v[38:39], v[6:7]
	v_pk_fma_f32 v[4:5], v[40:41], v[40:41], v[4:5]
	v_pk_fma_f32 v[6:7], v[42:43], v[42:43], v[6:7]
	v_pk_fma_f32 v[4:5], v[44:45], v[44:45], v[4:5]
	v_pk_fma_f32 v[6:7], v[46:47], v[46:47], v[6:7]
	v_pk_add_f32 v[4:5], v[4:5], v[6:7]
	v_add_f32_e32 v22, v4, v5
	ds_bpermute_b32 v23, v16, v22
	s_waitcnt lgkmcnt(0)
	v_add_f32_e32 v22, v22, v23
	ds_bpermute_b32 v23, v17, v22
	s_waitcnt lgkmcnt(0)
	v_add_f32_e32 v22, v22, v23
	ds_bpermute_b32 v23, v18, v22
	s_waitcnt lgkmcnt(0)
	v_add_f32_e32 v22, v22, v23
	ds_bpermute_b32 v23, v19, v22
	s_waitcnt lgkmcnt(0)
	v_add_f32_e32 v22, v22, v23
	ds_bpermute_b32 v23, v20, v22
	s_waitcnt lgkmcnt(0)
	v_add_f32_e32 v22, v22, v23
	ds_bpermute_b32 v23, v21, v22
	s_waitcnt lgkmcnt(0)
	v_add_f32_e32 v22, v22, v23
	v_fmamk_f32 v22, v22, 0x3a800000, v26
	v_rsq_f32_e32 v24, v22
	s_nop 0
	s_waitcnt vmcnt(4)
	v_pk_mul_f32 v[32:33], v[32:33], v[24:25] op_sel_hi:[1,0]
	v_pk_mul_f32 v[34:35], v[34:35], v[24:25] op_sel_hi:[1,0]
	v_pk_add_f32 v[98:99], v[98:99], 1.0 op_sel_hi:[1,0]
	v_pk_add_f32 v[100:101], v[100:101], 1.0 op_sel_hi:[1,0]
	v_pk_mul_f32 v[32:33], v[64:65], v[32:33]
	v_pk_mul_f32 v[34:35], v[66:67], v[34:35]
	v_pk_fma_f32 v[32:33], v[98:99], v[32:33], v[82:83]
	v_pk_fma_f32 v[34:35], v[100:101], v[34:35], v[84:85]
	v_cvt_pk_bf16_f32 v32, v32, v33
	v_cvt_pk_bf16_f32 v33, v34, v35
	global_store_dwordx2 v3, v[32:33], s[18:19]
	v_pk_mul_f32 v[36:37], v[36:37], v[24:25] op_sel_hi:[1,0]
	v_pk_mul_f32 v[38:39], v[38:39], v[24:25] op_sel_hi:[1,0]
	v_pk_add_f32 v[102:103], v[102:103], 1.0 op_sel_hi:[1,0]
	v_pk_add_f32 v[104:105], v[104:105], 1.0 op_sel_hi:[1,0]
	v_pk_mul_f32 v[36:37], v[68:69], v[36:37]
	v_pk_mul_f32 v[38:39], v[70:71], v[38:39]
	v_pk_fma_f32 v[36:37], v[102:103], v[36:37], v[86:87]
	v_pk_fma_f32 v[38:39], v[104:105], v[38:39], v[88:89]
	v_cvt_pk_bf16_f32 v36, v36, v37
	v_cvt_pk_bf16_f32 v37, v38, v39
	global_store_dwordx2 v3, v[36:37], s[18:19] offset:512
	v_pk_mul_f32 v[40:41], v[40:41], v[24:25] op_sel_hi:[1,0]
	v_pk_mul_f32 v[42:43], v[42:43], v[24:25] op_sel_hi:[1,0]
	v_pk_add_f32 v[106:107], v[106:107], 1.0 op_sel_hi:[1,0]
	v_pk_add_f32 v[108:109], v[108:109], 1.0 op_sel_hi:[1,0]
	v_pk_mul_f32 v[40:41], v[72:73], v[40:41]
	v_pk_mul_f32 v[42:43], v[74:75], v[42:43]
	v_pk_fma_f32 v[40:41], v[106:107], v[40:41], v[90:91]
	v_pk_fma_f32 v[42:43], v[108:109], v[42:43], v[92:93]
	v_cvt_pk_bf16_f32 v40, v40, v41
	v_cvt_pk_bf16_f32 v41, v42, v43
	global_store_dwordx2 v3, v[40:41], s[18:19] offset:1024
	v_pk_mul_f32 v[44:45], v[44:45], v[24:25] op_sel_hi:[1,0]
	v_pk_mul_f32 v[46:47], v[46:47], v[24:25] op_sel_hi:[1,0]
	v_pk_add_f32 v[110:111], v[110:111], 1.0 op_sel_hi:[1,0]
	v_pk_add_f32 v[112:113], v[112:113], 1.0 op_sel_hi:[1,0]
	v_pk_mul_f32 v[44:45], v[76:77], v[44:45]
	v_pk_mul_f32 v[46:47], v[78:79], v[46:47]
	v_pk_fma_f32 v[44:45], v[110:111], v[44:45], v[94:95]
	v_pk_fma_f32 v[46:47], v[112:113], v[46:47], v[96:97]
	v_cvt_pk_bf16_f32 v44, v44, v45
	v_cvt_pk_bf16_f32 v45, v46, v47
	global_store_dwordx2 v3, v[44:45], s[18:19] offset:1536
	s_add_i32 s1, s1, s0
	s_cmp_lt_u32 s1, 0x2000
	s_cbranch_scc0 .Lnorm0_done
	s_sub_i32 s16, s1, 0x1000
	s_ashr_i32 s16, s16, 10
	s_add_i32 s16, s16, 1
	s_cmp_lt_u32 s1, 0x1000
	s_cselect_b32 s16, 0, s16
	s_mul_i32 s16, s16, 0x3000
	s_add_u32 s16, s4, s16
	s_addc_u32 s17, s5, 0
	global_load_dwordx4 v[82:85], v1, s[16:17]
	global_load_dwordx4 v[86:89], v1, s[16:17] offset:1024
	global_load_dwordx4 v[90:93], v1, s[16:17] offset:2048
	global_load_dwordx4 v[94:97], v1, s[16:17] offset:3072
	s_add_u32 s16, s16, 0x1000
	s_addc_u32 s17, s17, 0
	global_load_dwordx4 v[98:101], v1, s[16:17]
	global_load_dwordx4 v[102:105], v1, s[16:17] offset:1024
	global_load_dwordx4 v[106:109], v1, s[16:17] offset:2048
	global_load_dwordx4 v[110:113], v1, s[16:17] offset:3072
	s_add_i32 s16, s1, s0
	s_cmp_lt_u32 s16, 0x2000
	s_cselect_b32 s17, s16, s1
	s_lshl_b32 s18, s17, 12
	s_cmp_lt_u32 s17, 0x1000
	s_cselect_b32 s10, s12, s14
	s_cselect_b32 s11, s13, s15
	s_cselect_b32 s19, 0, 0x1000000
	s_sub_u32 s18, s18, s19
	s_add_u32 s10, s10, s18
	s_addc_u32 s11, s11, 0
	global_load_dwordx4 v[32:35], v1, s[10:11]
	global_load_dwordx4 v[36:39], v1, s[10:11] offset:1024
	global_load_dwordx4 v[40:43], v1, s[10:11] offset:2048
	global_load_dwordx4 v[44:47], v1, s[10:11] offset:3072
	s_lshl_b32 s18, s1, 11
	s_add_u32 s18, s2, s18
	s_addc_u32 s19, s3, 0
	s_waitcnt vmcnt(16)
	v_pk_mul_f32 v[4:5], v[48:49], v[48:49]
	v_pk_mul_f32 v[6:7], v[50:51], v[50:51]
	v_pk_fma_f32 v[4:5], v[52:53], v[52:53], v[4:5]
	v_pk_fma_f32 v[6:7], v[54:55], v[54:55], v[6:7]
	v_pk_fma_f32 v[4:5], v[56:57], v[56:57], v[4:5]
	v_pk_fma_f32 v[6:7], v[58:59], v[58:59], v[6:7]
	v_pk_fma_f32 v[4:5], v[60:61], v[60:61], v[4:5]
	v_pk_fma_f32 v[6:7], v[62:63], v[62:63], v[6:7]
	v_pk_add_f32 v[4:5], v[4:5], v[6:7]
	v_add_f32_e32 v22, v4, v5
	ds_bpermute_b32 v23, v16, v22
	s_waitcnt lgkmcnt(0)
	v_add_f32_e32 v22, v22, v23
	ds_bpermute_b32 v23, v17, v22
	s_waitcnt lgkmcnt(0)
	v_add_f32_e32 v22, v22, v23
	ds_bpermute_b32 v23, v18, v22
	s_waitcnt lgkmcnt(0)
	v_add_f32_e32 v22, v22, v23
	ds_bpermute_b32 v23, v19, v22
	s_waitcnt lgkmcnt(0)
	v_add_f32_e32 v22, v22, v23
	ds_bpermute_b32 v23, v20, v22
	s_waitcnt lgkmcnt(0)
	v_add_f32_e32 v22, v22, v23
	ds_bpermute_b32 v23, v21, v22
	s_waitcnt lgkmcnt(0)
	v_add_f32_e32 v22, v22, v23
	v_fmamk_f32 v22, v22, 0x3a800000, v26
	v_rsq_f32_e32 v24, v22
	s_nop 0
	s_waitcnt vmcnt(4)
	v_pk_mul_f32 v[48:49], v[48:49], v[24:25] op_sel_hi:[1,0]
	v_pk_mul_f32 v[50:51], v[50:51], v[24:25] op_sel_hi:[1,0]
	v_pk_add_f32 v[98:99], v[98:99], 1.0 op_sel_hi:[1,0]
	v_pk_add_f32 v[100:101], v[100:101], 1.0 op_sel_hi:[1,0]
	v_pk_mul_f32 v[48:49], v[64:65], v[48:49]
	v_pk_mul_f32 v[50:51], v[66:67], v[50:51]
	v_pk_fma_f32 v[48:49], v[98:99], v[48:49], v[82:83]
	v_pk_fma_f32 v[50:51], v[100:101], v[50:51], v[84:85]
	v_cvt_pk_bf16_f32 v48, v48, v49
	v_cvt_pk_bf16_f32 v49, v50, v51
	global_store_dwordx2 v3, v[48:49], s[18:19]
	v_pk_mul_f32 v[52:53], v[52:53], v[24:25] op_sel_hi:[1,0]
	v_pk_mul_f32 v[54:55], v[54:55], v[24:25] op_sel_hi:[1,0]
	v_pk_add_f32 v[102:103], v[102:103], 1.0 op_sel_hi:[1,0]
	v_pk_add_f32 v[104:105], v[104:105], 1.0 op_sel_hi:[1,0]
	v_pk_mul_f32 v[52:53], v[68:69], v[52:53]
	v_pk_mul_f32 v[54:55], v[70:71], v[54:55]
	v_pk_fma_f32 v[52:53], v[102:103], v[52:53], v[86:87]
	v_pk_fma_f32 v[54:55], v[104:105], v[54:55], v[88:89]
	v_cvt_pk_bf16_f32 v52, v52, v53
	v_cvt_pk_bf16_f32 v53, v54, v55
	global_store_dwordx2 v3, v[52:53], s[18:19] offset:512
	v_pk_mul_f32 v[56:57], v[56:57], v[24:25] op_sel_hi:[1,0]
	v_pk_mul_f32 v[58:59], v[58:59], v[24:25] op_sel_hi:[1,0]
	v_pk_add_f32 v[106:107], v[106:107], 1.0 op_sel_hi:[1,0]
	v_pk_add_f32 v[108:109], v[108:109], 1.0 op_sel_hi:[1,0]
	v_pk_mul_f32 v[56:57], v[72:73], v[56:57]
	v_pk_mul_f32 v[58:59], v[74:75], v[58:59]
	v_pk_fma_f32 v[56:57], v[106:107], v[56:57], v[90:91]
	v_pk_fma_f32 v[58:59], v[108:109], v[58:59], v[92:93]
	v_cvt_pk_bf16_f32 v56, v56, v57
	v_cvt_pk_bf16_f32 v57, v58, v59
	global_store_dwordx2 v3, v[56:57], s[18:19] offset:1024
	v_pk_mul_f32 v[60:61], v[60:61], v[24:25] op_sel_hi:[1,0]
	v_pk_mul_f32 v[62:63], v[62:63], v[24:25] op_sel_hi:[1,0]
	v_pk_add_f32 v[110:111], v[110:111], 1.0 op_sel_hi:[1,0]
	v_pk_add_f32 v[112:113], v[112:113], 1.0 op_sel_hi:[1,0]
	v_pk_mul_f32 v[60:61], v[76:77], v[60:61]
	v_pk_mul_f32 v[62:63], v[78:79], v[62:63]
	v_pk_fma_f32 v[60:61], v[110:111], v[60:61], v[94:95]
	v_pk_fma_f32 v[62:63], v[112:113], v[62:63], v[96:97]
	v_cvt_pk_bf16_f32 v60, v60, v61
	v_cvt_pk_bf16_f32 v61, v62, v63
	global_store_dwordx2 v3, v[60:61], s[18:19] offset:1536
	s_add_i32 s1, s1, s0
	s_cmp_lt_u32 s1, 0x2000
	s_cbranch_scc1 .Lnorm0_a
.Lnorm0_done:
	s_waitcnt vmcnt(0)
	v_readlane_b32 s0, v253, 0
	v_readlane_b32 s1, v253, 1
	s_load_dwordx2 s[0:1], s[0:1], 0x160
	s_waitcnt lgkmcnt(0)
	v_mov_b64_e32 v[80:81], s[0:1]
.LBB0_200:
	s_or_b64 exec, exec, s[6:7]
	s_movk_i32 s0, 0x544
	v_cmp_gt_i32_e32 vcc, s0, v150
	v_and_b32_e32 v156, 63, v146
	s_and_saveexec_b64 s[8:9], vcc
	s_cbranch_execz .LBB0_231
	v_mbcnt_hi_u32_b32 v140, -1, v145
	v_readlane_b32 s2, v253, 0
	v_readlane_b32 s3, v253, 1
	s_load_dwordx2 s[10:11], s[2:3], 0x168
	s_load_dwordx2 s[4:5], s[2:3], 0x160
	v_lshlrev_b32_e32 v141, 5, v140
	v_readfirstlane_b32 s1, v150
	s_waitcnt lgkmcnt(0)
	s_lshl_b32 s0, s10, 2
.Lsw_task:
	s_mov_b32 s10, 5
	s_mov_b32 s11, s1
	s_mov_b32 s12, 0x7700000
	s_cmp_lt_u32 s1, 0x200
	s_cbranch_scc1 .Lsw_dec
	s_mov_b32 s10, 10
	s_sub_u32 s11, s1, 0x200
	s_mov_b32 s12, 0x7f00000
	s_cmp_lt_u32 s1, 0x404
	s_cbranch_scc1 .Lsw_dec
	s_mov_b32 s10, 15
	s_sub_u32 s11, s1, 0x404
	s_mov_b32 s12, 0x8740000
.Lsw_dec:
	s_mul_i32 s13, s10, 0x3000
	s_add_u32 s14, s4, 0xf440000
	s_addc_u32 s15, s5, 0
	s_add_u32 s14, s14, s13
	s_addc_u32 s15, s15, 0
	v_lshlrev_b32_e32 v139, 6, v140
	global_load_dwordx4 v[0:3], v139, s[14:15]
	global_load_dwordx4 v[4:7], v139, s[14:15] offset:16
	global_load_dwordx4 v[8:11], v139, s[14:15] offset:32
	global_load_dwordx4 v[12:15], v139, s[14:15] offset:48
	s_add_u32 s14, s14, 0x3000
	s_addc_u32 s15, s15, 0
	global_load_dwordx4 v[16:19], v139, s[14:15]
	global_load_dwordx4 v[20:23], v139, s[14:15] offset:16
	global_load_dwordx4 v[24:27], v139, s[14:15] offset:32
	global_load_dwordx4 v[28:31], v139, s[14:15] offset:48
	s_add_u32 s14, s14, 0x3000
	s_addc_u32 s15, s15, 0
	global_load_dwordx4 v[32:35], v139, s[14:15]
	global_load_dwordx4 v[36:39], v139, s[14:15] offset:16
	global_load_dwordx4 v[40:43], v139, s[14:15] offset:32
	global_load_dwordx4 v[44:47], v139, s[14:15] offset:48
	s_add_u32 s14, s14, 0x3000
	s_addc_u32 s15, s15, 0
	global_load_dwordx4 v[48:51], v139, s[14:15]
	global_load_dwordx4 v[52:55], v139, s[14:15] offset:16
	global_load_dwordx4 v[56:59], v139, s[14:15] offset:32
	global_load_dwordx4 v[60:63], v139, s[14:15] offset:48
	s_add_u32 s14, s14, 0x3000
	s_addc_u32 s15, s15, 0
	global_load_dwordx4 v[64:67], v139, s[14:15]
	global_load_dwordx4 v[68:71], v139, s[14:15] offset:16
	global_load_dwordx4 v[72:75], v139, s[14:15] offset:32
	global_load_dwordx4 v[76:79], v139, s[14:15] offset:48
	s_lshl_b32 s16, s11, 14
	s_add_u32 s16, s16, s12
	s_add_u32 s16, s4, s16
	s_addc_u32 s17, s5, 0
	s_mul_i32 s18, s10, 0x4200
	s_lshl_b32 s19, s11, 5
	s_add_u32 s18, s18, s19
	s_add_u32 s18, s18, 0xfaa2100
	s_add_u32 s18, s4, s18
	s_addc_u32 s19, s5, 0
	global_load_dwordx4 v[82:85], v141, s[16:17]
	global_load_dwordx4 v[86:89], v141, s[16:17] offset:16
	global_load_dwordx4 v[90:93], v141, s[16:17] offset:2048
	global_load_dwordx4 v[94:97], v141, s[16:17] offset:2064
	s_add_u32 s16, s16, 0x1000
	s_addc_u32 s17, s17, 0
	global_load_dwordx4 v[98:101], v141, s[16:17]
	global_load_dwordx4 v[102:105], v141, s[16:17] offset:16
	global_load_dwordx4 v[106:109], v141, s[16:17] offset:2048
	global_load_dwordx4 v[110:113], v141, s[16:17] offset:2064
	s_waitcnt vmcnt(4)
	v_lshlrev_b32_e32 v114, 16, v82
	v_and_b32_e32 v115, 0xffff0000, v82
	v_lshlrev_b32_e32 v116, 16, v83
	v_and_b32_e32 v117, 0xffff0000, v83
	v_lshlrev_b32_e32 v118, 16, v84
	v_and_b32_e32 v119, 0xffff0000, v84
	v_lshlrev_b32_e32 v120, 16, v85
	v_and_b32_e32 v121, 0xffff0000, v85
	v_lshlrev_b32_e32 v122, 16, v86
	v_and_b32_e32 v123, 0xffff0000, v86
	v_lshlrev_b32_e32 v124, 16, v87
	v_and_b32_e32 v125, 0xffff0000, v87
	v_lshlrev_b32_e32 v126, 16, v88
	v_and_b32_e32 v127, 0xffff0000, v88
	v_lshlrev_b32_e32 v128, 16, v89
	v_and_b32_e32 v129, 0xffff0000, v89
	v_fma_f32 v130, v0, v114, 0
	v_fma_f32 v131, v16, v114, 0
	v_fma_f32 v132, v32, v114, 0
	v_fma_f32 v133, v48, v114, 0
	v_fma_f32 v134, v64, v114, 0
	v_fmac_f32_e32 v130, v1, v115
	v_fmac_f32_e32 v131, v17, v115
	v_fmac_f32_e32 v132, v33, v115
	v_fmac_f32_e32 v133, v49, v115
	v_fmac_f32_e32 v134, v65, v115
	v_fmac_f32_e32 v130, v2, v116
	v_fmac_f32_e32 v131, v18, v116
	v_fmac_f32_e32 v132, v34, v116
	v_fmac_f32_e32 v133, v50, v116
	v_fmac_f32_e32 v134, v66, v116
	v_fmac_f32_e32 v130, v3, v117
	v_fmac_f32_e32 v131, v19, v117
	v_fmac_f32_e32 v132, v35, v117
	v_fmac_f32_e32 v133, v51, v117
	v_fmac_f32_e32 v134, v67, v117
	v_fmac_f32_e32 v130, v4, v118
	v_fmac_f32_e32 v131, v20, v118
	v_fmac_f32_e32 v132, v36, v118
	v_fmac_f32_e32 v133, v52, v118
	v_fmac_f32_e32 v134, v68, v118
	v_fmac_f32_e32 v130, v5, v119
	v_fmac_f32_e32 v131, v21, v119
	v_fmac_f32_e32 v132, v37, v119
	v_fmac_f32_e32 v133, v53, v119
	v_fmac_f32_e32 v134, v69, v119
	v_fmac_f32_e32 v130, v6, v120
	v_fmac_f32_e32 v131, v22, v120
	v_fmac_f32_e32 v132, v38, v120
	v_fmac_f32_e32 v133, v54, v120
	v_fmac_f32_e32 v134, v70, v120
	v_fmac_f32_e32 v130, v7, v121
	v_fmac_f32_e32 v131, v23, v121
	v_fmac_f32_e32 v132, v39, v121
	v_fmac_f32_e32 v133, v55, v121
	v_fmac_f32_e32 v134, v71, v121
	v_fmac_f32_e32 v130, v8, v122
	v_fmac_f32_e32 v131, v24, v122
	v_fmac_f32_e32 v132, v40, v122
	v_fmac_f32_e32 v133, v56, v122
	v_fmac_f32_e32 v134, v72, v122
	v_fmac_f32_e32 v130, v9, v123
	v_fmac_f32_e32 v131, v25, v123
	v_fmac_f32_e32 v132, v41, v123
	v_fmac_f32_e32 v133, v57, v123
	v_fmac_f32_e32 v134, v73, v123
	v_fmac_f32_e32 v130, v10, v124
	v_fmac_f32_e32 v131, v26, v124
	v_fmac_f32_e32 v132, v42, v124
	v_fmac_f32_e32 v133, v58, v124
	v_fmac_f32_e32 v134, v74, v124
	v_fmac_f32_e32 v130, v11, v125
	v_fmac_f32_e32 v131, v27, v125
	v_fmac_f32_e32 v132, v43, v125
	v_fmac_f32_e32 v133, v59, v125
	v_fmac_f32_e32 v134, v75, v125
	v_fmac_f32_e32 v130, v12, v126
	v_fmac_f32_e32 v131, v28, v126
	v_fmac_f32_e32 v132, v44, v126
	v_fmac_f32_e32 v133, v60, v126
	v_fmac_f32_e32 v134, v76, v126
	v_fmac_f32_e32 v130, v13, v127
	v_fmac_f32_e32 v131, v29, v127
	v_fmac_f32_e32 v132, v45, v127
	v_fmac_f32_e32 v133, v61, v127
	v_fmac_f32_e32 v134, v77, v127
	v_fmac_f32_e32 v130, v14, v128
	v_fmac_f32_e32 v131, v30, v128
	v_fmac_f32_e32 v132, v46, v128
	v_fmac_f32_e32 v133, v62, v128
	v_fmac_f32_e32 v134, v78, v128
	v_fmac_f32_e32 v130, v15, v129
	v_fmac_f32_e32 v131, v31, v129
	v_fmac_f32_e32 v132, v47, v129
	v_fmac_f32_e32 v133, v63, v129
	v_fmac_f32_e32 v134, v79, v129
	v_lshlrev_b32_e32 v114, 16, v90
	v_and_b32_e32 v115, 0xffff0000, v90
	v_lshlrev_b32_e32 v116, 16, v91
	v_and_b32_e32 v117, 0xffff0000, v91
	v_lshlrev_b32_e32 v118, 16, v92
	v_and_b32_e32 v119, 0xffff0000, v92
	v_lshlrev_b32_e32 v120, 16, v93
	v_and_b32_e32 v121, 0xffff0000, v93
	v_lshlrev_b32_e32 v122, 16, v94
	v_and_b32_e32 v123, 0xffff0000, v94
	v_lshlrev_b32_e32 v124, 16, v95
	v_and_b32_e32 v125, 0xffff0000, v95
	v_lshlrev_b32_e32 v126, 16, v96
	v_and_b32_e32 v127, 0xffff0000, v96
	v_lshlrev_b32_e32 v128, 16, v97
	v_and_b32_e32 v129, 0xffff0000, v97
	v_fma_f32 v135, v0, v114, 0
	v_fma_f32 v136, v16, v114, 0
	v_fma_f32 v137, v32, v114, 0
	v_fma_f32 v138, v48, v114, 0
	v_fma_f32 v139, v64, v114, 0
	v_fmac_f32_e32 v135, v1, v115
	v_fmac_f32_e32 v136, v17, v115
	v_fmac_f32_e32 v137, v33, v115
	v_fmac_f32_e32 v138, v49, v115
	v_fmac_f32_e32 v139, v65, v115
	v_fmac_f32_e32 v135, v2, v116
	v_fmac_f32_e32 v136, v18, v116
	v_fmac_f32_e32 v137, v34, v116
	v_fmac_f32_e32 v138, v50, v116
	v_fmac_f32_e32 v139, v66, v116
	v_fmac_f32_e32 v135, v3, v117
	v_fmac_f32_e32 v136, v19, v117
	v_fmac_f32_e32 v137, v35, v117
	v_fmac_f32_e32 v138, v51, v117
	v_fmac_f32_e32 v139, v67, v117
	v_fmac_f32_e32 v135, v4, v118
	v_fmac_f32_e32 v136, v20, v118
	v_fmac_f32_e32 v137, v36, v118
	v_fmac_f32_e32 v138, v52, v118
	v_fmac_f32_e32 v139, v68, v118
	v_fmac_f32_e32 v135, v5, v119
	v_fmac_f32_e32 v136, v21, v119
	v_fmac_f32_e32 v137, v37, v119
	v_fmac_f32_e32 v138, v53, v119
	v_fmac_f32_e32 v139, v69, v119
	v_fmac_f32_e32 v135, v6, v120
	v_fmac_f32_e32 v136, v22, v120
	v_fmac_f32_e32 v137, v38, v120
	v_fmac_f32_e32 v138, v54, v120
	v_fmac_f32_e32 v139, v70, v120
	v_fmac_f32_e32 v135, v7, v121
	v_fmac_f32_e32 v136, v23, v121
	v_fmac_f32_e32 v137, v39, v121
	v_fmac_f32_e32 v138, v55, v121
	v_fmac_f32_e32 v139, v71, v121
	v_fmac_f32_e32 v135, v8, v122
	v_fmac_f32_e32 v136, v24, v122
	v_fmac_f32_e32 v137, v40, v122
	v_fmac_f32_e32 v138, v56, v122
	v_fmac_f32_e32 v139, v72, v122
	v_fmac_f32_e32 v135, v9, v123
	v_fmac_f32_e32 v136, v25, v123
	v_fmac_f32_e32 v137, v41, v123
	v_fmac_f32_e32 v138, v57, v123
	v_fmac_f32_e32 v139, v73, v123
	v_fmac_f32_e32 v135, v10, v124
	v_fmac_f32_e32 v136, v26, v124
	v_fmac_f32_e32 v137, v42, v124
	v_fmac_f32_e32 v138, v58, v124
	v_fmac_f32_e32 v139, v74, v124
	v_fmac_f32_e32 v135, v11, v125
	v_fmac_f32_e32 v136, v27, v125
	v_fmac_f32_e32 v137, v43, v125
	v_fmac_f32_e32 v138, v59, v125
	v_fmac_f32_e32 v139, v75, v125
	v_fmac_f32_e32 v135, v12, v126
	v_fmac_f32_e32 v136, v28, v126
	v_fmac_f32_e32 v137, v44, v126
	v_fmac_f32_e32 v138, v60, v126
	v_fmac_f32_e32 v139, v76, v126
	v_fmac_f32_e32 v135, v13, v127
	v_fmac_f32_e32 v136, v29, v127
	v_fmac_f32_e32 v137, v45, v127
	v_fmac_f32_e32 v138, v61, v127
	v_fmac_f32_e32 v139, v77, v127
	v_fmac_f32_e32 v135, v14, v128
	v_fmac_f32_e32 v136, v30, v128
	v_fmac_f32_e32 v137, v46, v128
	v_fmac_f32_e32 v138, v62, v128
	v_fmac_f32_e32 v139, v78, v128
	v_fmac_f32_e32 v135, v15, v129
	v_fmac_f32_e32 v136, v31, v129
	v_fmac_f32_e32 v137, v47, v129
	v_fmac_f32_e32 v138, v63, v129
	v_fmac_f32_e32 v139, v79, v129
	v_xor_b32_e32 v124, 32, v140
	v_lshlrev_b32_e32 v124, 2, v124
	v_xor_b32_e32 v125, 16, v140
	v_lshlrev_b32_e32 v125, 2, v125
	v_xor_b32_e32 v126, 8, v140
	v_lshlrev_b32_e32 v126, 2, v126
	v_xor_b32_e32 v127, 4, v140
	v_lshlrev_b32_e32 v127, 2, v127
	v_xor_b32_e32 v128, 2, v140
	v_lshlrev_b32_e32 v128, 2, v128
	v_xor_b32_e32 v129, 1, v140
	v_lshlrev_b32_e32 v129, 2, v129
	ds_bpermute_b32 v114, v124, v130
	ds_bpermute_b32 v115, v124, v131
	ds_bpermute_b32 v116, v124, v132
	ds_bpermute_b32 v117, v124, v133
	ds_bpermute_b32 v118, v124, v134
	ds_bpermute_b32 v119, v124, v135
	ds_bpermute_b32 v120, v124, v136
	ds_bpermute_b32 v121, v124, v137
	ds_bpermute_b32 v122, v124, v138
	ds_bpermute_b32 v123, v124, v139
	s_waitcnt lgkmcnt(0)
	v_add_f32_e32 v130, v130, v114
	v_add_f32_e32 v131, v131, v115
	v_add_f32_e32 v132, v132, v116
	v_add_f32_e32 v133, v133, v117
	v_add_f32_e32 v134, v134, v118
	v_add_f32_e32 v135, v135, v119
	v_add_f32_e32 v136, v136, v120
	v_add_f32_e32 v137, v137, v121
	v_add_f32_e32 v138, v138, v122
	v_add_f32_e32 v139, v139, v123
	ds_bpermute_b32 v114, v125, v130
	ds_bpermute_b32 v115, v125, v131
	ds_bpermute_b32 v116, v125, v132
	ds_bpermute_b32 v117, v125, v133
	ds_bpermute_b32 v118, v125, v134
	ds_bpermute_b32 v119, v125, v135
	ds_bpermute_b32 v120, v125, v136
	ds_bpermute_b32 v121, v125, v137
	ds_bpermute_b32 v122, v125, v138
	ds_bpermute_b32 v123, v125, v139
	s_waitcnt lgkmcnt(0)
	v_add_f32_e32 v130, v130, v114
	v_add_f32_e32 v131, v131, v115
	v_add_f32_e32 v132, v132, v116
	v_add_f32_e32 v133, v133, v117
	v_add_f32_e32 v134, v134, v118
	v_add_f32_e32 v135, v135, v119
	v_add_f32_e32 v136, v136, v120
	v_add_f32_e32 v137, v137, v121
	v_add_f32_e32 v138, v138, v122
	v_add_f32_e32 v139, v139, v123
	ds_bpermute_b32 v114, v126, v130
	ds_bpermute_b32 v115, v126, v131
	ds_bpermute_b32 v116, v126, v132
	ds_bpermute_b32 v117, v126, v133
	ds_bpermute_b32 v118, v126, v134
	ds_bpermute_b32 v119, v126, v135
	ds_bpermute_b32 v120, v126, v136
	ds_bpermute_b32 v121, v126, v137
	ds_bpermute_b32 v122, v126, v138
	ds_bpermute_b32 v123, v126, v139
	s_waitcnt lgkmcnt(0)
	v_add_f32_e32 v130, v130, v114
	v_add_f32_e32 v131, v131, v115
	v_add_f32_e32 v132, v132, v116
	v_add_f32_e32 v133, v133, v117
	v_add_f32_e32 v134, v134, v118
	v_add_f32_e32 v135, v135, v119
	v_add_f32_e32 v136, v136, v120
	v_add_f32_e32 v137, v137, v121
	v_add_f32_e32 v138, v138, v122
	v_add_f32_e32 v139, v139, v123
	ds_bpermute_b32 v114, v127, v130
	ds_bpermute_b32 v115, v127, v131
	ds_bpermute_b32 v116, v127, v132
	ds_bpermute_b32 v117, v127, v133
	ds_bpermute_b32 v118, v127, v134
	ds_bpermute_b32 v119, v127, v135
	ds_bpermute_b32 v120, v127, v136
	ds_bpermute_b32 v121, v127, v137
	ds_bpermute_b32 v122, v127, v138
	ds_bpermute_b32 v123, v127, v139
	s_waitcnt lgkmcnt(0)
	v_add_f32_e32 v130, v130, v114
	v_add_f32_e32 v131, v131, v115
	v_add_f32_e32 v132, v132, v116
	v_add_f32_e32 v133, v133, v117
	v_add_f32_e32 v134, v134, v118
	v_add_f32_e32 v135, v135, v119
	v_add_f32_e32 v136, v136, v120
	v_add_f32_e32 v137, v137, v121
	v_add_f32_e32 v138, v138, v122
	v_add_f32_e32 v139, v139, v123
	ds_bpermute_b32 v114, v128, v130
	ds_bpermute_b32 v115, v128, v131
	ds_bpermute_b32 v116, v128, v132
	ds_bpermute_b32 v117, v128, v133
	ds_bpermute_b32 v118, v128, v134
	ds_bpermute_b32 v119, v128, v135
	ds_bpermute_b32 v120, v128, v136
	ds_bpermute_b32 v121, v128, v137
	ds_bpermute_b32 v122, v128, v138
	ds_bpermute_b32 v123, v128, v139
	s_waitcnt lgkmcnt(0)
	v_add_f32_e32 v130, v130, v114
	v_add_f32_e32 v131, v131, v115
	v_add_f32_e32 v132, v132, v116
	v_add_f32_e32 v133, v133, v117
	v_add_f32_e32 v134, v134, v118
	v_add_f32_e32 v135, v135, v119
	v_add_f32_e32 v136, v136, v120
	v_add_f32_e32 v137, v137, v121
	v_add_f32_e32 v138, v138, v122
	v_add_f32_e32 v139, v139, v123
	ds_bpermute_b32 v114, v129, v130
	ds_bpermute_b32 v115, v129, v131
	ds_bpermute_b32 v116, v129, v132
	ds_bpermute_b32 v117, v129, v133
	ds_bpermute_b32 v118, v129, v134
	ds_bpermute_b32 v119, v129, v135
	ds_bpermute_b32 v120, v129, v136
	ds_bpermute_b32 v121, v129, v137
	ds_bpermute_b32 v122, v129, v138
	ds_bpermute_b32 v123, v129, v139
	s_waitcnt lgkmcnt(0)
	v_add_f32_e32 v130, v130, v114
	v_add_f32_e32 v131, v131, v115
	v_add_f32_e32 v132, v132, v116
	v_add_f32_e32 v133, v133, v117
	v_add_f32_e32 v134, v134, v118
	v_add_f32_e32 v135, v135, v119
	v_add_f32_e32 v136, v136, v120
	v_add_f32_e32 v137, v137, v121
	v_add_f32_e32 v138, v138, v122
	v_add_f32_e32 v139, v139, v123
	s_mov_b64 s[20:21], exec
	s_mov_b64 exec, 1
	v_mov_b32_e32 v114, 0x0
	global_store_dword v114, v130, s[18:19] offset:0
	global_store_dword v114, v135, s[18:19] offset:4
	v_mov_b32_e32 v114, 0x4200
	global_store_dword v114, v131, s[18:19] offset:0
	global_store_dword v114, v136, s[18:19] offset:4
	v_mov_b32_e32 v114, 0x8400
	global_store_dword v114, v132, s[18:19] offset:0
	global_store_dword v114, v137, s[18:19] offset:4
	v_mov_b32_e32 v114, 0xc600
	global_store_dword v114, v133, s[18:19] offset:0
	global_store_dword v114, v138, s[18:19] offset:4
	v_mov_b32_e32 v114, 0x10800
	global_store_dword v114, v134, s[18:19] offset:0
	global_store_dword v114, v139, s[18:19] offset:4
	s_mov_b64 exec, s[20:21]
	s_add_u32 s16, s16, 0x1000
	s_addc_u32 s17, s17, 0
	global_load_dwordx4 v[82:85], v141, s[16:17]
	global_load_dwordx4 v[86:89], v141, s[16:17] offset:16
	global_load_dwordx4 v[90:93], v141, s[16:17] offset:2048
	global_load_dwordx4 v[94:97], v141, s[16:17] offset:2064
	s_waitcnt vmcnt(14)
	v_lshlrev_b32_e32 v114, 16, v98
	v_and_b32_e32 v115, 0xffff0000, v98
	v_lshlrev_b32_e32 v116, 16, v99
	v_and_b32_e32 v117, 0xffff0000, v99
	v_lshlrev_b32_e32 v118, 16, v100
	v_and_b32_e32 v119, 0xffff0000, v100
	v_lshlrev_b32_e32 v120, 16, v101
	v_and_b32_e32 v121, 0xffff0000, v101
	v_lshlrev_b32_e32 v122, 16, v102
	v_and_b32_e32 v123, 0xffff0000, v102
	v_lshlrev_b32_e32 v124, 16, v103
	v_and_b32_e32 v125, 0xffff0000, v103
	v_lshlrev_b32_e32 v126, 16, v104
	v_and_b32_e32 v127, 0xffff0000, v104
	v_lshlrev_b32_e32 v128, 16, v105
	v_and_b32_e32 v129, 0xffff0000, v105
	v_fma_f32 v130, v0, v114, 0
	v_fma_f32 v131, v16, v114, 0
	v_fma_f32 v132, v32, v114, 0
	v_fma_f32 v133, v48, v114, 0
	v_fma_f32 v134, v64, v114, 0
	v_fmac_f32_e32 v130, v1, v115
	v_fmac_f32_e32 v131, v17, v115
	v_fmac_f32_e32 v132, v33, v115
	v_fmac_f32_e32 v133, v49, v115
	v_fmac_f32_e32 v134, v65, v115
	v_fmac_f32_e32 v130, v2, v116
	v_fmac_f32_e32 v131, v18, v116
	v_fmac_f32_e32 v132, v34, v116
	v_fmac_f32_e32 v133, v50, v116
	v_fmac_f32_e32 v134, v66, v116
	v_fmac_f32_e32 v130, v3, v117
	v_fmac_f32_e32 v131, v19, v117
	v_fmac_f32_e32 v132, v35, v117
	v_fmac_f32_e32 v133, v51, v117
	v_fmac_f32_e32 v134, v67, v117
	v_fmac_f32_e32 v130, v4, v118
	v_fmac_f32_e32 v131, v20, v118
	v_fmac_f32_e32 v132, v36, v118
	v_fmac_f32_e32 v133, v52, v118
	v_fmac_f32_e32 v134, v68, v118
	v_fmac_f32_e32 v130, v5, v119
	v_fmac_f32_e32 v131, v21, v119
	v_fmac_f32_e32 v132, v37, v119
	v_fmac_f32_e32 v133, v53, v119
	v_fmac_f32_e32 v134, v69, v119
	v_fmac_f32_e32 v130, v6, v120
	v_fmac_f32_e32 v131, v22, v120
	v_fmac_f32_e32 v132, v38, v120
	v_fmac_f32_e32 v133, v54, v120
	v_fmac_f32_e32 v134, v70, v120
	v_fmac_f32_e32 v130, v7, v121
	v_fmac_f32_e32 v131, v23, v121
	v_fmac_f32_e32 v132, v39, v121
	v_fmac_f32_e32 v133, v55, v121
	v_fmac_f32_e32 v134, v71, v121
	v_fmac_f32_e32 v130, v8, v122
	v_fmac_f32_e32 v131, v24, v122
	v_fmac_f32_e32 v132, v40, v122
	v_fmac_f32_e32 v133, v56, v122
	v_fmac_f32_e32 v134, v72, v122
	v_fmac_f32_e32 v130, v9, v123
	v_fmac_f32_e32 v131, v25, v123
	v_fmac_f32_e32 v132, v41, v123
	v_fmac_f32_e32 v133, v57, v123
	v_fmac_f32_e32 v134, v73, v123
	v_fmac_f32_e32 v130, v10, v124
	v_fmac_f32_e32 v131, v26, v124
	v_fmac_f32_e32 v132, v42, v124
	v_fmac_f32_e32 v133, v58, v124
	v_fmac_f32_e32 v134, v74, v124
	v_fmac_f32_e32 v130, v11, v125
	v_fmac_f32_e32 v131, v27, v125
	v_fmac_f32_e32 v132, v43, v125
	v_fmac_f32_e32 v133, v59, v125
	v_fmac_f32_e32 v134, v75, v125
	v_fmac_f32_e32 v130, v12, v126
	v_fmac_f32_e32 v131, v28, v126
	v_fmac_f32_e32 v132, v44, v126
	v_fmac_f32_e32 v133, v60, v126
	v_fmac_f32_e32 v134, v76, v126
	v_fmac_f32_e32 v130, v13, v127
	v_fmac_f32_e32 v131, v29, v127
	v_fmac_f32_e32 v132, v45, v127
	v_fmac_f32_e32 v133, v61, v127
	v_fmac_f32_e32 v134, v77, v127
	v_fmac_f32_e32 v130, v14, v128
	v_fmac_f32_e32 v131, v30, v128
	v_fmac_f32_e32 v132, v46, v128
	v_fmac_f32_e32 v133, v62, v128
	v_fmac_f32_e32 v134, v78, v128
	v_fmac_f32_e32 v130, v15, v129
	v_fmac_f32_e32 v131, v31, v129
	v_fmac_f32_e32 v132, v47, v129
	v_fmac_f32_e32 v133, v63, v129
	v_fmac_f32_e32 v134, v79, v129
	v_lshlrev_b32_e32 v114, 16, v106
	v_and_b32_e32 v115, 0xffff0000, v106
	v_lshlrev_b32_e32 v116, 16, v107
	v_and_b32_e32 v117, 0xffff0000, v107
	v_lshlrev_b32_e32 v118, 16, v108
	v_and_b32_e32 v119, 0xffff0000, v108
	v_lshlrev_b32_e32 v120, 16, v109
	v_and_b32_e32 v121, 0xffff0000, v109
	v_lshlrev_b32_e32 v122, 16, v110
	v_and_b32_e32 v123, 0xffff0000, v110
	v_lshlrev_b32_e32 v124, 16, v111
	v_and_b32_e32 v125, 0xffff0000, v111
	v_lshlrev_b32_e32 v126, 16, v112
	v_and_b32_e32 v127, 0xffff0000, v112
	v_lshlrev_b32_e32 v128, 16, v113
	v_and_b32_e32 v129, 0xffff0000, v113
	v_fma_f32 v135, v0, v114, 0
	v_fma_f32 v136, v16, v114, 0
	v_fma_f32 v137, v32, v114, 0
	v_fma_f32 v138, v48, v114, 0
	v_fma_f32 v139, v64, v114, 0
	v_fmac_f32_e32 v135, v1, v115
	v_fmac_f32_e32 v136, v17, v115
	v_fmac_f32_e32 v137, v33, v115
	v_fmac_f32_e32 v138, v49, v115
	v_fmac_f32_e32 v139, v65, v115
	v_fmac_f32_e32 v135, v2, v116
	v_fmac_f32_e32 v136, v18, v116
	v_fmac_f32_e32 v137, v34, v116
	v_fmac_f32_e32 v138, v50, v116
	v_fmac_f32_e32 v139, v66, v116
	v_fmac_f32_e32 v135, v3, v117
	v_fmac_f32_e32 v136, v19, v117
	v_fmac_f32_e32 v137, v35, v117
	v_fmac_f32_e32 v138, v51, v117
	v_fmac_f32_e32 v139, v67, v117
	v_fmac_f32_e32 v135, v4, v118
	v_fmac_f32_e32 v136, v20, v118
	v_fmac_f32_e32 v137, v36, v118
	v_fmac_f32_e32 v138, v52, v118
	v_fmac_f32_e32 v139, v68, v118
	v_fmac_f32_e32 v135, v5, v119
	v_fmac_f32_e32 v136, v21, v119
	v_fmac_f32_e32 v137, v37, v119
	v_fmac_f32_e32 v138, v53, v119
	v_fmac_f32_e32 v139, v69, v119
	v_fmac_f32_e32 v135, v6, v120
	v_fmac_f32_e32 v136, v22, v120
	v_fmac_f32_e32 v137, v38, v120
	v_fmac_f32_e32 v138, v54, v120
	v_fmac_f32_e32 v139, v70, v120
	v_fmac_f32_e32 v135, v7, v121
	v_fmac_f32_e32 v136, v23, v121
	v_fmac_f32_e32 v137, v39, v121
	v_fmac_f32_e32 v138, v55, v121
	v_fmac_f32_e32 v139, v71, v121
	v_fmac_f32_e32 v135, v8, v122
	v_fmac_f32_e32 v136, v24, v122
	v_fmac_f32_e32 v137, v40, v122
	v_fmac_f32_e32 v138, v56, v122
	v_fmac_f32_e32 v139, v72, v122
	v_fmac_f32_e32 v135, v9, v123
	v_fmac_f32_e32 v136, v25, v123
	v_fmac_f32_e32 v137, v41, v123
	v_fmac_f32_e32 v138, v57, v123
	v_fmac_f32_e32 v139, v73, v123
	v_fmac_f32_e32 v135, v10, v124
	v_fmac_f32_e32 v136, v26, v124
	v_fmac_f32_e32 v137, v42, v124
	v_fmac_f32_e32 v138, v58, v124
	v_fmac_f32_e32 v139, v74, v124
	v_fmac_f32_e32 v135, v11, v125
	v_fmac_f32_e32 v136, v27, v125
	v_fmac_f32_e32 v137, v43, v125
	v_fmac_f32_e32 v138, v59, v125
	v_fmac_f32_e32 v139, v75, v125
	v_fmac_f32_e32 v135, v12, v126
	v_fmac_f32_e32 v136, v28, v126
	v_fmac_f32_e32 v137, v44, v126
	v_fmac_f32_e32 v138, v60, v126
	v_fmac_f32_e32 v139, v76, v126
	v_fmac_f32_e32 v135, v13, v127
	v_fmac_f32_e32 v136, v29, v127
	v_fmac_f32_e32 v137, v45, v127
	v_fmac_f32_e32 v138, v61, v127
	v_fmac_f32_e32 v139, v77, v127
	v_fmac_f32_e32 v135, v14, v128
	v_fmac_f32_e32 v136, v30, v128
	v_fmac_f32_e32 v137, v46, v128
	v_fmac_f32_e32 v138, v62, v128
	v_fmac_f32_e32 v139, v78, v128
	v_fmac_f32_e32 v135, v15, v129
	v_fmac_f32_e32 v136, v31, v129
	v_fmac_f32_e32 v137, v47, v129
	v_fmac_f32_e32 v138, v63, v129
	v_fmac_f32_e32 v139, v79, v129
	v_xor_b32_e32 v124, 32, v140
	v_lshlrev_b32_e32 v124, 2, v124
	v_xor_b32_e32 v125, 16, v140
	v_lshlrev_b32_e32 v125, 2, v125
	v_xor_b32_e32 v126, 8, v140
	v_lshlrev_b32_e32 v126, 2, v126
	v_xor_b32_e32 v127, 4, v140
	v_lshlrev_b32_e32 v127, 2, v127
	v_xor_b32_e32 v128, 2, v140
	v_lshlrev_b32_e32 v128, 2, v128
	v_xor_b32_e32 v129, 1, v140
	v_lshlrev_b32_e32 v129, 2, v129
	ds_bpermute_b32 v114, v124, v130
	ds_bpermute_b32 v115, v124, v131
	ds_bpermute_b32 v116, v124, v132
	ds_bpermute_b32 v117, v124, v133
	ds_bpermute_b32 v118, v124, v134
	ds_bpermute_b32 v119, v124, v135
	ds_bpermute_b32 v120, v124, v136
	ds_bpermute_b32 v121, v124, v137
	ds_bpermute_b32 v122, v124, v138
	ds_bpermute_b32 v123, v124, v139
	s_waitcnt lgkmcnt(0)
	v_add_f32_e32 v130, v130, v114
	v_add_f32_e32 v131, v131, v115
	v_add_f32_e32 v132, v132, v116
	v_add_f32_e32 v133, v133, v117
	v_add_f32_e32 v134, v134, v118
	v_add_f32_e32 v135, v135, v119
	v_add_f32_e32 v136, v136, v120
	v_add_f32_e32 v137, v137, v121
	v_add_f32_e32 v138, v138, v122
	v_add_f32_e32 v139, v139, v123
	ds_bpermute_b32 v114, v125, v130
	ds_bpermute_b32 v115, v125, v131
	ds_bpermute_b32 v116, v125, v132
	ds_bpermute_b32 v117, v125, v133
	ds_bpermute_b32 v118, v125, v134
	ds_bpermute_b32 v119, v125, v135
	ds_bpermute_b32 v120, v125, v136
	ds_bpermute_b32 v121, v125, v137
	ds_bpermute_b32 v122, v125, v138
	ds_bpermute_b32 v123, v125, v139
	s_waitcnt lgkmcnt(0)
	v_add_f32_e32 v130, v130, v114
	v_add_f32_e32 v131, v131, v115
	v_add_f32_e32 v132, v132, v116
	v_add_f32_e32 v133, v133, v117
	v_add_f32_e32 v134, v134, v118
	v_add_f32_e32 v135, v135, v119
	v_add_f32_e32 v136, v136, v120
	v_add_f32_e32 v137, v137, v121
	v_add_f32_e32 v138, v138, v122
	v_add_f32_e32 v139, v139, v123
	ds_bpermute_b32 v114, v126, v130
	ds_bpermute_b32 v115, v126, v131
	ds_bpermute_b32 v116, v126, v132
	ds_bpermute_b32 v117, v126, v133
	ds_bpermute_b32 v118, v126, v134
	ds_bpermute_b32 v119, v126, v135
	ds_bpermute_b32 v120, v126, v136
	ds_bpermute_b32 v121, v126, v137
	ds_bpermute_b32 v122, v126, v138
	ds_bpermute_b32 v123, v126, v139
	s_waitcnt lgkmcnt(0)
	v_add_f32_e32 v130, v130, v114
	v_add_f32_e32 v131, v131, v115
	v_add_f32_e32 v132, v132, v116
	v_add_f32_e32 v133, v133, v117
	v_add_f32_e32 v134, v134, v118
	v_add_f32_e32 v135, v135, v119
	v_add_f32_e32 v136, v136, v120
	v_add_f32_e32 v137, v137, v121
	v_add_f32_e32 v138, v138, v122
	v_add_f32_e32 v139, v139, v123
	ds_bpermute_b32 v114, v127, v130
	ds_bpermute_b32 v115, v127, v131
	ds_bpermute_b32 v116, v127, v132
	ds_bpermute_b32 v117, v127, v133
	ds_bpermute_b32 v118, v127, v134
	ds_bpermute_b32 v119, v127, v135
	ds_bpermute_b32 v120, v127, v136
	ds_bpermute_b32 v121, v127, v137
	ds_bpermute_b32 v122, v127, v138
	ds_bpermute_b32 v123, v127, v139
	s_waitcnt lgkmcnt(0)
	v_add_f32_e32 v130, v130, v114
	v_add_f32_e32 v131, v131, v115
	v_add_f32_e32 v132, v132, v116
	v_add_f32_e32 v133, v133, v117
	v_add_f32_e32 v134, v134, v118
	v_add_f32_e32 v135, v135, v119
	v_add_f32_e32 v136, v136, v120
	v_add_f32_e32 v137, v137, v121
	v_add_f32_e32 v138, v138, v122
	v_add_f32_e32 v139, v139, v123
	ds_bpermute_b32 v114, v128, v130
	ds_bpermute_b32 v115, v128, v131
	ds_bpermute_b32 v116, v128, v132
	ds_bpermute_b32 v117, v128, v133
	ds_bpermute_b32 v118, v128, v134
	ds_bpermute_b32 v119, v128, v135
	ds_bpermute_b32 v120, v128, v136
	ds_bpermute_b32 v121, v128, v137
	ds_bpermute_b32 v122, v128, v138
	ds_bpermute_b32 v123, v128, v139
	s_waitcnt lgkmcnt(0)
	v_add_f32_e32 v130, v130, v114
	v_add_f32_e32 v131, v131, v115
	v_add_f32_e32 v132, v132, v116
	v_add_f32_e32 v133, v133, v117
	v_add_f32_e32 v134, v134, v118
	v_add_f32_e32 v135, v135, v119
	v_add_f32_e32 v136, v136, v120
	v_add_f32_e32 v137, v137, v121
	v_add_f32_e32 v138, v138, v122
	v_add_f32_e32 v139, v139, v123
	ds_bpermute_b32 v114, v129, v130
	ds_bpermute_b32 v115, v129, v131
	ds_bpermute_b32 v116, v129, v132
	ds_bpermute_b32 v117, v129, v133
	ds_bpermute_b32 v118, v129, v134
	ds_bpermute_b32 v119, v129, v135
	ds_bpermute_b32 v120, v129, v136
	ds_bpermute_b32 v121, v129, v137
	ds_bpermute_b32 v122, v129, v138
	ds_bpermute_b32 v123, v129, v139
	s_waitcnt lgkmcnt(0)
	v_add_f32_e32 v130, v130, v114
	v_add_f32_e32 v131, v131, v115
	v_add_f32_e32 v132, v132, v116
	v_add_f32_e32 v133, v133, v117
	v_add_f32_e32 v134, v134, v118
	v_add_f32_e32 v135, v135, v119
	v_add_f32_e32 v136, v136, v120
	v_add_f32_e32 v137, v137, v121
	v_add_f32_e32 v138, v138, v122
	v_add_f32_e32 v139, v139, v123
	s_mov_b64 s[20:21], exec
	s_mov_b64 exec, 1
	v_mov_b32_e32 v114, 0x0
	global_store_dword v114, v130, s[18:19] offset:8
	global_store_dword v114, v135, s[18:19] offset:12
	v_mov_b32_e32 v114, 0x4200
	global_store_dword v114, v131, s[18:19] offset:8
	global_store_dword v114, v136, s[18:19] offset:12
	v_mov_b32_e32 v114, 0x8400
	global_store_dword v114, v132, s[18:19] offset:8
	global_store_dword v114, v137, s[18:19] offset:12
	v_mov_b32_e32 v114, 0xc600
	global_store_dword v114, v133, s[18:19] offset:8
	global_store_dword v114, v138, s[18:19] offset:12
	v_mov_b32_e32 v114, 0x10800
	global_store_dword v114, v134, s[18:19] offset:8
	global_store_dword v114, v139, s[18:19] offset:12
	s_mov_b64 exec, s[20:21]
	s_add_u32 s16, s16, 0x1000
	s_addc_u32 s17, s17, 0
	global_load_dwordx4 v[98:101], v141, s[16:17]
	global_load_dwordx4 v[102:105], v141, s[16:17] offset:16
	global_load_dwordx4 v[106:109], v141, s[16:17] offset:2048
	global_load_dwordx4 v[110:113], v141, s[16:17] offset:2064
	s_waitcnt vmcnt(14)
	v_lshlrev_b32_e32 v114, 16, v82
	v_and_b32_e32 v115, 0xffff0000, v82
	v_lshlrev_b32_e32 v116, 16, v83
	v_and_b32_e32 v117, 0xffff0000, v83
	v_lshlrev_b32_e32 v118, 16, v84
	v_and_b32_e32 v119, 0xffff0000, v84
	v_lshlrev_b32_e32 v120, 16, v85
	v_and_b32_e32 v121, 0xffff0000, v85
	v_lshlrev_b32_e32 v122, 16, v86
	v_and_b32_e32 v123, 0xffff0000, v86
	v_lshlrev_b32_e32 v124, 16, v87
	v_and_b32_e32 v125, 0xffff0000, v87
	v_lshlrev_b32_e32 v126, 16, v88
	v_and_b32_e32 v127, 0xffff0000, v88
	v_lshlrev_b32_e32 v128, 16, v89
	v_and_b32_e32 v129, 0xffff0000, v89
	v_fma_f32 v130, v0, v114, 0
	v_fma_f32 v131, v16, v114, 0
	v_fma_f32 v132, v32, v114, 0
	v_fma_f32 v133, v48, v114, 0
	v_fma_f32 v134, v64, v114, 0
	v_fmac_f32_e32 v130, v1, v115
	v_fmac_f32_e32 v131, v17, v115
	v_fmac_f32_e32 v132, v33, v115
	v_fmac_f32_e32 v133, v49, v115
	v_fmac_f32_e32 v134, v65, v115
	v_fmac_f32_e32 v130, v2, v116
	v_fmac_f32_e32 v131, v18, v116
	v_fmac_f32_e32 v132, v34, v116
	v_fmac_f32_e32 v133, v50, v116
	v_fmac_f32_e32 v134, v66, v116
	v_fmac_f32_e32 v130, v3, v117
	v_fmac_f32_e32 v131, v19, v117
	v_fmac_f32_e32 v132, v35, v117
	v_fmac_f32_e32 v133, v51, v117
	v_fmac_f32_e32 v134, v67, v117
	v_fmac_f32_e32 v130, v4, v118
	v_fmac_f32_e32 v131, v20, v118
	v_fmac_f32_e32 v132, v36, v118
	v_fmac_f32_e32 v133, v52, v118
	v_fmac_f32_e32 v134, v68, v118
	v_fmac_f32_e32 v130, v5, v119
	v_fmac_f32_e32 v131, v21, v119
	v_fmac_f32_e32 v132, v37, v119
	v_fmac_f32_e32 v133, v53, v119
	v_fmac_f32_e32 v134, v69, v119
	v_fmac_f32_e32 v130, v6, v120
	v_fmac_f32_e32 v131, v22, v120
	v_fmac_f32_e32 v132, v38, v120
	v_fmac_f32_e32 v133, v54, v120
	v_fmac_f32_e32 v134, v70, v120
	v_fmac_f32_e32 v130, v7, v121
	v_fmac_f32_e32 v131, v23, v121
	v_fmac_f32_e32 v132, v39, v121
	v_fmac_f32_e32 v133, v55, v121
	v_fmac_f32_e32 v134, v71, v121
	v_fmac_f32_e32 v130, v8, v122
	v_fmac_f32_e32 v131, v24, v122
	v_fmac_f32_e32 v132, v40, v122
	v_fmac_f32_e32 v133, v56, v122
	v_fmac_f32_e32 v134, v72, v122
	v_fmac_f32_e32 v130, v9, v123
	v_fmac_f32_e32 v131, v25, v123
	v_fmac_f32_e32 v132, v41, v123
	v_fmac_f32_e32 v133, v57, v123
	v_fmac_f32_e32 v134, v73, v123
	v_fmac_f32_e32 v130, v10, v124
	v_fmac_f32_e32 v131, v26, v124
	v_fmac_f32_e32 v132, v42, v124
	v_fmac_f32_e32 v133, v58, v124
	v_fmac_f32_e32 v134, v74, v124
	v_fmac_f32_e32 v130, v11, v125
	v_fmac_f32_e32 v131, v27, v125
	v_fmac_f32_e32 v132, v43, v125
	v_fmac_f32_e32 v133, v59, v125
	v_fmac_f32_e32 v134, v75, v125
	v_fmac_f32_e32 v130, v12, v126
	v_fmac_f32_e32 v131, v28, v126
	v_fmac_f32_e32 v132, v44, v126
	v_fmac_f32_e32 v133, v60, v126
	v_fmac_f32_e32 v134, v76, v126
	v_fmac_f32_e32 v130, v13, v127
	v_fmac_f32_e32 v131, v29, v127
	v_fmac_f32_e32 v132, v45, v127
	v_fmac_f32_e32 v133, v61, v127
	v_fmac_f32_e32 v134, v77, v127
	v_fmac_f32_e32 v130, v14, v128
	v_fmac_f32_e32 v131, v30, v128
	v_fmac_f32_e32 v132, v46, v128
	v_fmac_f32_e32 v133, v62, v128
	v_fmac_f32_e32 v134, v78, v128
	v_fmac_f32_e32 v130, v15, v129
	v_fmac_f32_e32 v131, v31, v129
	v_fmac_f32_e32 v132, v47, v129
	v_fmac_f32_e32 v133, v63, v129
	v_fmac_f32_e32 v134, v79, v129
	v_lshlrev_b32_e32 v114, 16, v90
	v_and_b32_e32 v115, 0xffff0000, v90
	v_lshlrev_b32_e32 v116, 16, v91
	v_and_b32_e32 v117, 0xffff0000, v91
	v_lshlrev_b32_e32 v118, 16, v92
	v_and_b32_e32 v119, 0xffff0000, v92
	v_lshlrev_b32_e32 v120, 16, v93
	v_and_b32_e32 v121, 0xffff0000, v93
	v_lshlrev_b32_e32 v122, 16, v94
	v_and_b32_e32 v123, 0xffff0000, v94
	v_lshlrev_b32_e32 v124, 16, v95
	v_and_b32_e32 v125, 0xffff0000, v95
	v_lshlrev_b32_e32 v126, 16, v96
	v_and_b32_e32 v127, 0xffff0000, v96
	v_lshlrev_b32_e32 v128, 16, v97
	v_and_b32_e32 v129, 0xffff0000, v97
	v_fma_f32 v135, v0, v114, 0
	v_fma_f32 v136, v16, v114, 0
	v_fma_f32 v137, v32, v114, 0
	v_fma_f32 v138, v48, v114, 0
	v_fma_f32 v139, v64, v114, 0
	v_fmac_f32_e32 v135, v1, v115
	v_fmac_f32_e32 v136, v17, v115
	v_fmac_f32_e32 v137, v33, v115
	v_fmac_f32_e32 v138, v49, v115
	v_fmac_f32_e32 v139, v65, v115
	v_fmac_f32_e32 v135, v2, v116
	v_fmac_f32_e32 v136, v18, v116
	v_fmac_f32_e32 v137, v34, v116
	v_fmac_f32_e32 v138, v50, v116
	v_fmac_f32_e32 v139, v66, v116
	v_fmac_f32_e32 v135, v3, v117
	v_fmac_f32_e32 v136, v19, v117
	v_fmac_f32_e32 v137, v35, v117
	v_fmac_f32_e32 v138, v51, v117
	v_fmac_f32_e32 v139, v67, v117
	v_fmac_f32_e32 v135, v4, v118
	v_fmac_f32_e32 v136, v20, v118
	v_fmac_f32_e32 v137, v36, v118
	v_fmac_f32_e32 v138, v52, v118
	v_fmac_f32_e32 v139, v68, v118
	v_fmac_f32_e32 v135, v5, v119
	v_fmac_f32_e32 v136, v21, v119
	v_fmac_f32_e32 v137, v37, v119
	v_fmac_f32_e32 v138, v53, v119
	v_fmac_f32_e32 v139, v69, v119
	v_fmac_f32_e32 v135, v6, v120
	v_fmac_f32_e32 v136, v22, v120
	v_fmac_f32_e32 v137, v38, v120
	v_fmac_f32_e32 v138, v54, v120
	v_fmac_f32_e32 v139, v70, v120
	v_fmac_f32_e32 v135, v7, v121
	v_fmac_f32_e32 v136, v23, v121
	v_fmac_f32_e32 v137, v39, v121
	v_fmac_f32_e32 v138, v55, v121
	v_fmac_f32_e32 v139, v71, v121
	v_fmac_f32_e32 v135, v8, v122
	v_fmac_f32_e32 v136, v24, v122
	v_fmac_f32_e32 v137, v40, v122
	v_fmac_f32_e32 v138, v56, v122
	v_fmac_f32_e32 v139, v72, v122
	v_fmac_f32_e32 v135, v9, v123
	v_fmac_f32_e32 v136, v25, v123
	v_fmac_f32_e32 v137, v41, v123
	v_fmac_f32_e32 v138, v57, v123
	v_fmac_f32_e32 v139, v73, v123
	v_fmac_f32_e32 v135, v10, v124
	v_fmac_f32_e32 v136, v26, v124
	v_fmac_f32_e32 v137, v42, v124
	v_fmac_f32_e32 v138, v58, v124
	v_fmac_f32_e32 v139, v74, v124
	v_fmac_f32_e32 v135, v11, v125
	v_fmac_f32_e32 v136, v27, v125
	v_fmac_f32_e32 v137, v43, v125
	v_fmac_f32_e32 v138, v59, v125
	v_fmac_f32_e32 v139, v75, v125
	v_fmac_f32_e32 v135, v12, v126
	v_fmac_f32_e32 v136, v28, v126
	v_fmac_f32_e32 v137, v44, v126
	v_fmac_f32_e32 v138, v60, v126
	v_fmac_f32_e32 v139, v76, v126
	v_fmac_f32_e32 v135, v13, v127
	v_fmac_f32_e32 v136, v29, v127
	v_fmac_f32_e32 v137, v45, v127
	v_fmac_f32_e32 v138, v61, v127
	v_fmac_f32_e32 v139, v77, v127
	v_fmac_f32_e32 v135, v14, v128
	v_fmac_f32_e32 v136, v30, v128
	v_fmac_f32_e32 v137, v46, v128
	v_fmac_f32_e32 v138, v62, v128
	v_fmac_f32_e32 v139, v78, v128
	v_fmac_f32_e32 v135, v15, v129
	v_fmac_f32_e32 v136, v31, v129
	v_fmac_f32_e32 v137, v47, v129
	v_fmac_f32_e32 v138, v63, v129
	v_fmac_f32_e32 v139, v79, v129
	v_xor_b32_e32 v124, 32, v140
	v_lshlrev_b32_e32 v124, 2, v124
	v_xor_b32_e32 v125, 16, v140
	v_lshlrev_b32_e32 v125, 2, v125
	v_xor_b32_e32 v126, 8, v140
	v_lshlrev_b32_e32 v126, 2, v126
	v_xor_b32_e32 v127, 4, v140
	v_lshlrev_b32_e32 v127, 2, v127
	v_xor_b32_e32 v128, 2, v140
	v_lshlrev_b32_e32 v128, 2, v128
	v_xor_b32_e32 v129, 1, v140
	v_lshlrev_b32_e32 v129, 2, v129
	ds_bpermute_b32 v114, v124, v130
	ds_bpermute_b32 v115, v124, v131
	ds_bpermute_b32 v116, v124, v132
	ds_bpermute_b32 v117, v124, v133
	ds_bpermute_b32 v118, v124, v134
	ds_bpermute_b32 v119, v124, v135
	ds_bpermute_b32 v120, v124, v136
	ds_bpermute_b32 v121, v124, v137
	ds_bpermute_b32 v122, v124, v138
	ds_bpermute_b32 v123, v124, v139
	s_waitcnt lgkmcnt(0)
	v_add_f32_e32 v130, v130, v114
	v_add_f32_e32 v131, v131, v115
	v_add_f32_e32 v132, v132, v116
	v_add_f32_e32 v133, v133, v117
	v_add_f32_e32 v134, v134, v118
	v_add_f32_e32 v135, v135, v119
	v_add_f32_e32 v136, v136, v120
	v_add_f32_e32 v137, v137, v121
	v_add_f32_e32 v138, v138, v122
	v_add_f32_e32 v139, v139, v123
	ds_bpermute_b32 v114, v125, v130
	ds_bpermute_b32 v115, v125, v131
	ds_bpermute_b32 v116, v125, v132
	ds_bpermute_b32 v117, v125, v133
	ds_bpermute_b32 v118, v125, v134
	ds_bpermute_b32 v119, v125, v135
	ds_bpermute_b32 v120, v125, v136
	ds_bpermute_b32 v121, v125, v137
	ds_bpermute_b32 v122, v125, v138
	ds_bpermute_b32 v123, v125, v139
	s_waitcnt lgkmcnt(0)
	v_add_f32_e32 v130, v130, v114
	v_add_f32_e32 v131, v131, v115
	v_add_f32_e32 v132, v132, v116
	v_add_f32_e32 v133, v133, v117
	v_add_f32_e32 v134, v134, v118
	v_add_f32_e32 v135, v135, v119
	v_add_f32_e32 v136, v136, v120
	v_add_f32_e32 v137, v137, v121
	v_add_f32_e32 v138, v138, v122
	v_add_f32_e32 v139, v139, v123
	ds_bpermute_b32 v114, v126, v130
	ds_bpermute_b32 v115, v126, v131
	ds_bpermute_b32 v116, v126, v132
	ds_bpermute_b32 v117, v126, v133
	ds_bpermute_b32 v118, v126, v134
	ds_bpermute_b32 v119, v126, v135
	ds_bpermute_b32 v120, v126, v136
	ds_bpermute_b32 v121, v126, v137
	ds_bpermute_b32 v122, v126, v138
	ds_bpermute_b32 v123, v126, v139
	s_waitcnt lgkmcnt(0)
	v_add_f32_e32 v130, v130, v114
	v_add_f32_e32 v131, v131, v115
	v_add_f32_e32 v132, v132, v116
	v_add_f32_e32 v133, v133, v117
	v_add_f32_e32 v134, v134, v118
	v_add_f32_e32 v135, v135, v119
	v_add_f32_e32 v136, v136, v120
	v_add_f32_e32 v137, v137, v121
	v_add_f32_e32 v138, v138, v122
	v_add_f32_e32 v139, v139, v123
	ds_bpermute_b32 v114, v127, v130
	ds_bpermute_b32 v115, v127, v131
	ds_bpermute_b32 v116, v127, v132
	ds_bpermute_b32 v117, v127, v133
	ds_bpermute_b32 v118, v127, v134
	ds_bpermute_b32 v119, v127, v135
	ds_bpermute_b32 v120, v127, v136
	ds_bpermute_b32 v121, v127, v137
	ds_bpermute_b32 v122, v127, v138
	ds_bpermute_b32 v123, v127, v139
	s_waitcnt lgkmcnt(0)
	v_add_f32_e32 v130, v130, v114
	v_add_f32_e32 v131, v131, v115
	v_add_f32_e32 v132, v132, v116
	v_add_f32_e32 v133, v133, v117
	v_add_f32_e32 v134, v134, v118
	v_add_f32_e32 v135, v135, v119
	v_add_f32_e32 v136, v136, v120
	v_add_f32_e32 v137, v137, v121
	v_add_f32_e32 v138, v138, v122
	v_add_f32_e32 v139, v139, v123
	ds_bpermute_b32 v114, v128, v130
	ds_bpermute_b32 v115, v128, v131
	ds_bpermute_b32 v116, v128, v132
	ds_bpermute_b32 v117, v128, v133
	ds_bpermute_b32 v118, v128, v134
	ds_bpermute_b32 v119, v128, v135
	ds_bpermute_b32 v120, v128, v136
	ds_bpermute_b32 v121, v128, v137
	ds_bpermute_b32 v122, v128, v138
	ds_bpermute_b32 v123, v128, v139
	s_waitcnt lgkmcnt(0)
	v_add_f32_e32 v130, v130, v114
	v_add_f32_e32 v131, v131, v115
	v_add_f32_e32 v132, v132, v116
	v_add_f32_e32 v133, v133, v117
	v_add_f32_e32 v134, v134, v118
	v_add_f32_e32 v135, v135, v119
	v_add_f32_e32 v136, v136, v120
	v_add_f32_e32 v137, v137, v121
	v_add_f32_e32 v138, v138, v122
	v_add_f32_e32 v139, v139, v123
	ds_bpermute_b32 v114, v129, v130
	ds_bpermute_b32 v115, v129, v131
	ds_bpermute_b32 v116, v129, v132
	ds_bpermute_b32 v117, v129, v133
	ds_bpermute_b32 v118, v129, v134
	ds_bpermute_b32 v119, v129, v135
	ds_bpermute_b32 v120, v129, v136
	ds_bpermute_b32 v121, v129, v137
	ds_bpermute_b32 v122, v129, v138
	ds_bpermute_b32 v123, v129, v139
	s_waitcnt lgkmcnt(0)
	v_add_f32_e32 v130, v130, v114
	v_add_f32_e32 v131, v131, v115
	v_add_f32_e32 v132, v132, v116
	v_add_f32_e32 v133, v133, v117
	v_add_f32_e32 v134, v134, v118
	v_add_f32_e32 v135, v135, v119
	v_add_f32_e32 v136, v136, v120
	v_add_f32_e32 v137, v137, v121
	v_add_f32_e32 v138, v138, v122
	v_add_f32_e32 v139, v139, v123
	s_mov_b64 s[20:21], exec
	s_mov_b64 exec, 1
	v_mov_b32_e32 v114, 0x0
	global_store_dword v114, v130, s[18:19] offset:16
	global_store_dword v114, v135, s[18:19] offset:20
	v_mov_b32_e32 v114, 0x4200
	global_store_dword v114, v131, s[18:19] offset:16
	global_store_dword v114, v136, s[18:19] offset:20
	v_mov_b32_e32 v114, 0x8400
	global_store_dword v114, v132, s[18:19] offset:16
	global_store_dword v114, v137, s[18:19] offset:20
	v_mov_b32_e32 v114, 0xc600
	global_store_dword v114, v133, s[18:19] offset:16
	global_store_dword v114, v138, s[18:19] offset:20
	v_mov_b32_e32 v114, 0x10800
	global_store_dword v114, v134, s[18:19] offset:16
	global_store_dword v114, v139, s[18:19] offset:20
	s_mov_b64 exec, s[20:21]
	s_waitcnt vmcnt(10)
	v_lshlrev_b32_e32 v114, 16, v98
	v_and_b32_e32 v115, 0xffff0000, v98
	v_lshlrev_b32_e32 v116, 16, v99
	v_and_b32_e32 v117, 0xffff0000, v99
	v_lshlrev_b32_e32 v118, 16, v100
	v_and_b32_e32 v119, 0xffff0000, v100
	v_lshlrev_b32_e32 v120, 16, v101
	v_and_b32_e32 v121, 0xffff0000, v101
	v_lshlrev_b32_e32 v122, 16, v102
	v_and_b32_e32 v123, 0xffff0000, v102
	v_lshlrev_b32_e32 v124, 16, v103
	v_and_b32_e32 v125, 0xffff0000, v103
	v_lshlrev_b32_e32 v126, 16, v104
	v_and_b32_e32 v127, 0xffff0000, v104
	v_lshlrev_b32_e32 v128, 16, v105
	v_and_b32_e32 v129, 0xffff0000, v105
	v_fma_f32 v130, v0, v114, 0
	v_fma_f32 v131, v16, v114, 0
	v_fma_f32 v132, v32, v114, 0
	v_fma_f32 v133, v48, v114, 0
	v_fma_f32 v134, v64, v114, 0
	v_fmac_f32_e32 v130, v1, v115
	v_fmac_f32_e32 v131, v17, v115
	v_fmac_f32_e32 v132, v33, v115
	v_fmac_f32_e32 v133, v49, v115
	v_fmac_f32_e32 v134, v65, v115
	v_fmac_f32_e32 v130, v2, v116
	v_fmac_f32_e32 v131, v18, v116
	v_fmac_f32_e32 v132, v34, v116
	v_fmac_f32_e32 v133, v50, v116
	v_fmac_f32_e32 v134, v66, v116
	v_fmac_f32_e32 v130, v3, v117
	v_fmac_f32_e32 v131, v19, v117
	v_fmac_f32_e32 v132, v35, v117
	v_fmac_f32_e32 v133, v51, v117
	v_fmac_f32_e32 v134, v67, v117
	v_fmac_f32_e32 v130, v4, v118
	v_fmac_f32_e32 v131, v20, v118
	v_fmac_f32_e32 v132, v36, v118
	v_fmac_f32_e32 v133, v52, v118
	v_fmac_f32_e32 v134, v68, v118
	v_fmac_f32_e32 v130, v5, v119
	v_fmac_f32_e32 v131, v21, v119
	v_fmac_f32_e32 v132, v37, v119
	v_fmac_f32_e32 v133, v53, v119
	v_fmac_f32_e32 v134, v69, v119
	v_fmac_f32_e32 v130, v6, v120
	v_fmac_f32_e32 v131, v22, v120
	v_fmac_f32_e32 v132, v38, v120
	v_fmac_f32_e32 v133, v54, v120
	v_fmac_f32_e32 v134, v70, v120
	v_fmac_f32_e32 v130, v7, v121
	v_fmac_f32_e32 v131, v23, v121
	v_fmac_f32_e32 v132, v39, v121
	v_fmac_f32_e32 v133, v55, v121
	v_fmac_f32_e32 v134, v71, v121
	v_fmac_f32_e32 v130, v8, v122
	v_fmac_f32_e32 v131, v24, v122
	v_fmac_f32_e32 v132, v40, v122
	v_fmac_f32_e32 v133, v56, v122
	v_fmac_f32_e32 v134, v72, v122
	v_fmac_f32_e32 v130, v9, v123
	v_fmac_f32_e32 v131, v25, v123
	v_fmac_f32_e32 v132, v41, v123
	v_fmac_f32_e32 v133, v57, v123
	v_fmac_f32_e32 v134, v73, v123
	v_fmac_f32_e32 v130, v10, v124
	v_fmac_f32_e32 v131, v26, v124
	v_fmac_f32_e32 v132, v42, v124
	v_fmac_f32_e32 v133, v58, v124
	v_fmac_f32_e32 v134, v74, v124
	v_fmac_f32_e32 v130, v11, v125
	v_fmac_f32_e32 v131, v27, v125
	v_fmac_f32_e32 v132, v43, v125
	v_fmac_f32_e32 v133, v59, v125
	v_fmac_f32_e32 v134, v75, v125
	v_fmac_f32_e32 v130, v12, v126
	v_fmac_f32_e32 v131, v28, v126
	v_fmac_f32_e32 v132, v44, v126
	v_fmac_f32_e32 v133, v60, v126
	v_fmac_f32_e32 v134, v76, v126
	v_fmac_f32_e32 v130, v13, v127
	v_fmac_f32_e32 v131, v29, v127
	v_fmac_f32_e32 v132, v45, v127
	v_fmac_f32_e32 v133, v61, v127
	v_fmac_f32_e32 v134, v77, v127
	v_fmac_f32_e32 v130, v14, v128
	v_fmac_f32_e32 v131, v30, v128
	v_fmac_f32_e32 v132, v46, v128
	v_fmac_f32_e32 v133, v62, v128
	v_fmac_f32_e32 v134, v78, v128
	v_fmac_f32_e32 v130, v15, v129
	v_fmac_f32_e32 v131, v31, v129
	v_fmac_f32_e32 v132, v47, v129
	v_fmac_f32_e32 v133, v63, v129
	v_fmac_f32_e32 v134, v79, v129
	v_lshlrev_b32_e32 v114, 16, v106
	v_and_b32_e32 v115, 0xffff0000, v106
	v_lshlrev_b32_e32 v116, 16, v107
	v_and_b32_e32 v117, 0xffff0000, v107
	v_lshlrev_b32_e32 v118, 16, v108
	v_and_b32_e32 v119, 0xffff0000, v108
	v_lshlrev_b32_e32 v120, 16, v109
	v_and_b32_e32 v121, 0xffff0000, v109
	v_lshlrev_b32_e32 v122, 16, v110
	v_and_b32_e32 v123, 0xffff0000, v110
	v_lshlrev_b32_e32 v124, 16, v111
	v_and_b32_e32 v125, 0xffff0000, v111
	v_lshlrev_b32_e32 v126, 16, v112
	v_and_b32_e32 v127, 0xffff0000, v112
	v_lshlrev_b32_e32 v128, 16, v113
	v_and_b32_e32 v129, 0xffff0000, v113
	v_fma_f32 v135, v0, v114, 0
	v_fma_f32 v136, v16, v114, 0
	v_fma_f32 v137, v32, v114, 0
	v_fma_f32 v138, v48, v114, 0
	v_fma_f32 v139, v64, v114, 0
	v_fmac_f32_e32 v135, v1, v115
	v_fmac_f32_e32 v136, v17, v115
	v_fmac_f32_e32 v137, v33, v115
	v_fmac_f32_e32 v138, v49, v115
	v_fmac_f32_e32 v139, v65, v115
	v_fmac_f32_e32 v135, v2, v116
	v_fmac_f32_e32 v136, v18, v116
	v_fmac_f32_e32 v137, v34, v116
	v_fmac_f32_e32 v138, v50, v116
	v_fmac_f32_e32 v139, v66, v116
	v_fmac_f32_e32 v135, v3, v117
	v_fmac_f32_e32 v136, v19, v117
	v_fmac_f32_e32 v137, v35, v117
	v_fmac_f32_e32 v138, v51, v117
	v_fmac_f32_e32 v139, v67, v117
	v_fmac_f32_e32 v135, v4, v118
	v_fmac_f32_e32 v136, v20, v118
	v_fmac_f32_e32 v137, v36, v118
	v_fmac_f32_e32 v138, v52, v118
	v_fmac_f32_e32 v139, v68, v118
	v_fmac_f32_e32 v135, v5, v119
	v_fmac_f32_e32 v136, v21, v119
	v_fmac_f32_e32 v137, v37, v119
	v_fmac_f32_e32 v138, v53, v119
	v_fmac_f32_e32 v139, v69, v119
	v_fmac_f32_e32 v135, v6, v120
	v_fmac_f32_e32 v136, v22, v120
	v_fmac_f32_e32 v137, v38, v120
	v_fmac_f32_e32 v138, v54, v120
	v_fmac_f32_e32 v139, v70, v120
	v_fmac_f32_e32 v135, v7, v121
	v_fmac_f32_e32 v136, v23, v121
	v_fmac_f32_e32 v137, v39, v121
	v_fmac_f32_e32 v138, v55, v121
	v_fmac_f32_e32 v139, v71, v121
	v_fmac_f32_e32 v135, v8, v122
	v_fmac_f32_e32 v136, v24, v122
	v_fmac_f32_e32 v137, v40, v122
	v_fmac_f32_e32 v138, v56, v122
	v_fmac_f32_e32 v139, v72, v122
	v_fmac_f32_e32 v135, v9, v123
	v_fmac_f32_e32 v136, v25, v123
	v_fmac_f32_e32 v137, v41, v123
	v_fmac_f32_e32 v138, v57, v123
	v_fmac_f32_e32 v139, v73, v123
	v_fmac_f32_e32 v135, v10, v124
	v_fmac_f32_e32 v136, v26, v124
	v_fmac_f32_e32 v137, v42, v124
	v_fmac_f32_e32 v138, v58, v124
	v_fmac_f32_e32 v139, v74, v124
	v_fmac_f32_e32 v135, v11, v125
	v_fmac_f32_e32 v136, v27, v125
	v_fmac_f32_e32 v137, v43, v125
	v_fmac_f32_e32 v138, v59, v125
	v_fmac_f32_e32 v139, v75, v125
	v_fmac_f32_e32 v135, v12, v126
	v_fmac_f32_e32 v136, v28, v126
	v_fmac_f32_e32 v137, v44, v126
	v_fmac_f32_e32 v138, v60, v126
	v_fmac_f32_e32 v139, v76, v126
	v_fmac_f32_e32 v135, v13, v127
	v_fmac_f32_e32 v136, v29, v127
	v_fmac_f32_e32 v137, v45, v127
	v_fmac_f32_e32 v138, v61, v127
	v_fmac_f32_e32 v139, v77, v127
	v_fmac_f32_e32 v135, v14, v128
	v_fmac_f32_e32 v136, v30, v128
	v_fmac_f32_e32 v137, v46, v128
	v_fmac_f32_e32 v138, v62, v128
	v_fmac_f32_e32 v139, v78, v128
	v_fmac_f32_e32 v135, v15, v129
	v_fmac_f32_e32 v136, v31, v129
	v_fmac_f32_e32 v137, v47, v129
	v_fmac_f32_e32 v138, v63, v129
	v_fmac_f32_e32 v139, v79, v129
	v_xor_b32_e32 v124, 32, v140
	v_lshlrev_b32_e32 v124, 2, v124
	v_xor_b32_e32 v125, 16, v140
	v_lshlrev_b32_e32 v125, 2, v125
	v_xor_b32_e32 v126, 8, v140
	v_lshlrev_b32_e32 v126, 2, v126
	v_xor_b32_e32 v127, 4, v140
	v_lshlrev_b32_e32 v127, 2, v127
	v_xor_b32_e32 v128, 2, v140
	v_lshlrev_b32_e32 v128, 2, v128
	v_xor_b32_e32 v129, 1, v140
	v_lshlrev_b32_e32 v129, 2, v129
	ds_bpermute_b32 v114, v124, v130
	ds_bpermute_b32 v115, v124, v131
	ds_bpermute_b32 v116, v124, v132
	ds_bpermute_b32 v117, v124, v133
	ds_bpermute_b32 v118, v124, v134
	ds_bpermute_b32 v119, v124, v135
	ds_bpermute_b32 v120, v124, v136
	ds_bpermute_b32 v121, v124, v137
	ds_bpermute_b32 v122, v124, v138
	ds_bpermute_b32 v123, v124, v139
	s_waitcnt lgkmcnt(0)
	v_add_f32_e32 v130, v130, v114
	v_add_f32_e32 v131, v131, v115
	v_add_f32_e32 v132, v132, v116
	v_add_f32_e32 v133, v133, v117
	v_add_f32_e32 v134, v134, v118
	v_add_f32_e32 v135, v135, v119
	v_add_f32_e32 v136, v136, v120
	v_add_f32_e32 v137, v137, v121
	v_add_f32_e32 v138, v138, v122
	v_add_f32_e32 v139, v139, v123
	ds_bpermute_b32 v114, v125, v130
	ds_bpermute_b32 v115, v125, v131
	ds_bpermute_b32 v116, v125, v132
	ds_bpermute_b32 v117, v125, v133
	ds_bpermute_b32 v118, v125, v134
	ds_bpermute_b32 v119, v125, v135
	ds_bpermute_b32 v120, v125, v136
	ds_bpermute_b32 v121, v125, v137
	ds_bpermute_b32 v122, v125, v138
	ds_bpermute_b32 v123, v125, v139
	s_waitcnt lgkmcnt(0)
	v_add_f32_e32 v130, v130, v114
	v_add_f32_e32 v131, v131, v115
	v_add_f32_e32 v132, v132, v116
	v_add_f32_e32 v133, v133, v117
	v_add_f32_e32 v134, v134, v118
	v_add_f32_e32 v135, v135, v119
	v_add_f32_e32 v136, v136, v120
	v_add_f32_e32 v137, v137, v121
	v_add_f32_e32 v138, v138, v122
	v_add_f32_e32 v139, v139, v123
	ds_bpermute_b32 v114, v126, v130
	ds_bpermute_b32 v115, v126, v131
	ds_bpermute_b32 v116, v126, v132
	ds_bpermute_b32 v117, v126, v133
	ds_bpermute_b32 v118, v126, v134
	ds_bpermute_b32 v119, v126, v135
	ds_bpermute_b32 v120, v126, v136
	ds_bpermute_b32 v121, v126, v137
	ds_bpermute_b32 v122, v126, v138
	ds_bpermute_b32 v123, v126, v139
	s_waitcnt lgkmcnt(0)
	v_add_f32_e32 v130, v130, v114
	v_add_f32_e32 v131, v131, v115
	v_add_f32_e32 v132, v132, v116
	v_add_f32_e32 v133, v133, v117
	v_add_f32_e32 v134, v134, v118
	v_add_f32_e32 v135, v135, v119
	v_add_f32_e32 v136, v136, v120
	v_add_f32_e32 v137, v137, v121
	v_add_f32_e32 v138, v138, v122
	v_add_f32_e32 v139, v139, v123
	ds_bpermute_b32 v114, v127, v130
	ds_bpermute_b32 v115, v127, v131
	ds_bpermute_b32 v116, v127, v132
	ds_bpermute_b32 v117, v127, v133
	ds_bpermute_b32 v118, v127, v134
	ds_bpermute_b32 v119, v127, v135
	ds_bpermute_b32 v120, v127, v136
	ds_bpermute_b32 v121, v127, v137
	ds_bpermute_b32 v122, v127, v138
	ds_bpermute_b32 v123, v127, v139
	s_waitcnt lgkmcnt(0)
	v_add_f32_e32 v130, v130, v114
	v_add_f32_e32 v131, v131, v115
	v_add_f32_e32 v132, v132, v116
	v_add_f32_e32 v133, v133, v117
	v_add_f32_e32 v134, v134, v118
	v_add_f32_e32 v135, v135, v119
	v_add_f32_e32 v136, v136, v120
	v_add_f32_e32 v137, v137, v121
	v_add_f32_e32 v138, v138, v122
	v_add_f32_e32 v139, v139, v123
	ds_bpermute_b32 v114, v128, v130
	ds_bpermute_b32 v115, v128, v131
	ds_bpermute_b32 v116, v128, v132
	ds_bpermute_b32 v117, v128, v133
	ds_bpermute_b32 v118, v128, v134
	ds_bpermute_b32 v119, v128, v135
	ds_bpermute_b32 v120, v128, v136
	ds_bpermute_b32 v121, v128, v137
	ds_bpermute_b32 v122, v128, v138
	ds_bpermute_b32 v123, v128, v139
	s_waitcnt lgkmcnt(0)
	v_add_f32_e32 v130, v130, v114
	v_add_f32_e32 v131, v131, v115
	v_add_f32_e32 v132, v132, v116
	v_add_f32_e32 v133, v133, v117
	v_add_f32_e32 v134, v134, v118
	v_add_f32_e32 v135, v135, v119
	v_add_f32_e32 v136, v136, v120
	v_add_f32_e32 v137, v137, v121
	v_add_f32_e32 v138, v138, v122
	v_add_f32_e32 v139, v139, v123
	ds_bpermute_b32 v114, v129, v130
	ds_bpermute_b32 v115, v129, v131
	ds_bpermute_b32 v116, v129, v132
	ds_bpermute_b32 v117, v129, v133
	ds_bpermute_b32 v118, v129, v134
	ds_bpermute_b32 v119, v129, v135
	ds_bpermute_b32 v120, v129, v136
	ds_bpermute_b32 v121, v129, v137
	ds_bpermute_b32 v122, v129, v138
	ds_bpermute_b32 v123, v129, v139
	s_waitcnt lgkmcnt(0)
	v_add_f32_e32 v130, v130, v114
	v_add_f32_e32 v131, v131, v115
	v_add_f32_e32 v132, v132, v116
	v_add_f32_e32 v133, v133, v117
	v_add_f32_e32 v134, v134, v118
	v_add_f32_e32 v135, v135, v119
	v_add_f32_e32 v136, v136, v120
	v_add_f32_e32 v137, v137, v121
	v_add_f32_e32 v138, v138, v122
	v_add_f32_e32 v139, v139, v123
	s_mov_b64 s[20:21], exec
	s_mov_b64 exec, 1
	v_mov_b32_e32 v114, 0x0
	global_store_dword v114, v130, s[18:19] offset:24
	global_store_dword v114, v135, s[18:19] offset:28
	v_mov_b32_e32 v114, 0x4200
	global_store_dword v114, v131, s[18:19] offset:24
	global_store_dword v114, v136, s[18:19] offset:28
	v_mov_b32_e32 v114, 0x8400
	global_store_dword v114, v132, s[18:19] offset:24
	global_store_dword v114, v137, s[18:19] offset:28
	v_mov_b32_e32 v114, 0xc600
	global_store_dword v114, v133, s[18:19] offset:24
	global_store_dword v114, v138, s[18:19] offset:28
	v_mov_b32_e32 v114, 0x10800
	global_store_dword v114, v134, s[18:19] offset:24
	global_store_dword v114, v139, s[18:19] offset:28
	s_mov_b64 exec, s[20:21]
	s_add_i32 s1, s1, s0
	s_cmp_lt_u32 s1, 0x544
	s_cbranch_scc1 .Lsw_task

.LBB0_387:
	s_setprio 0
	s_cmp_ge_i32 s4, s33
	s_cbranch_scc1 .Lattna_fast
	s_and_b64 vcc, s[88:89], exec
	s_cbranch_scc0 .Lattna_fast
	s_cmp_lt_i32 s4, s33
	v_add_u32_e32 v199, s5, v175
	s_cselect_b64 s[10:11], -1, 0
	v_add_u32_e32 v200, 0xffffff81, v199
	s_and_b64 vcc, s[88:89], s[10:11]
	v_cmp_gt_u32_e64 s[10:11], s76, v200
	s_cmp_lt_i32 s8, s33
	s_cselect_b64 s[12:13], -1, 0
	v_cndmask_b32_e64 v200, v130, v244, s[10:11]
	v_cndmask_b32_e32 v130, v130, v200, vcc
	v_add_u32_e32 v200, 0xffffff82, v199
	v_cmp_gt_u32_e64 s[14:15], s76, v200
	s_and_b64 s[12:13], s[88:89], s[12:13]
	v_add_u32_e32 v198, 0xffffff7f, v199
	v_cndmask_b32_e64 v200, v131, v244, s[14:15]
	v_cndmask_b32_e32 v131, v131, v200, vcc
	v_add_u32_e32 v200, 0xffffff8f, v199
	v_cmp_gt_u32_e64 s[16:17], s76, v200
	v_cmp_gt_u32_e64 s[6:7], s76, v198
	s_nop 0
	v_cndmask_b32_e64 v200, v140, v244, s[16:17]
	v_cndmask_b32_e32 v140, v140, v200, vcc
	v_add_u32_e32 v200, 0xffffff90, v199
	v_cmp_gt_u32_e64 s[18:19], s76, v200
	v_cndmask_b32_e64 v198, v128, v244, s[6:7]
	v_cndmask_b32_e32 v128, v128, v198, vcc
	v_cndmask_b32_e64 v200, v141, v244, s[18:19]
	v_cndmask_b32_e32 v141, v141, v200, vcc
	v_add_u32_e32 v200, 0xffffff91, v199
	v_cmp_gt_u32_e64 s[20:21], s76, v200
	v_add_u32_e32 v198, 0xffffff80, v199
	v_cmp_gt_u32_e64 s[8:9], s76, v198
	v_cndmask_b32_e64 v200, v142, v244, s[20:21]
	v_cndmask_b32_e32 v142, v142, v200, vcc
	v_add_u32_e32 v200, 0xffffff92, v199
	v_cmp_gt_u32_e64 s[22:23], s76, v200
	v_cndmask_b32_e64 v198, v129, v244, s[8:9]
	v_cndmask_b32_e32 v129, v129, v198, vcc
	v_cndmask_b32_e64 v200, v143, v244, s[22:23]
	v_cndmask_b32_e32 v143, v143, v200, vcc
	v_add_u32_e32 v200, 0xffffff9f, v199
	v_cmp_gt_u32_e64 s[24:25], s76, v200
	v_max3_f32 v198, v128, s77, v129
	v_max3_f32 v198, v198, v130, v131
	v_cndmask_b32_e64 v200, v136, v244, s[24:25]
	v_cndmask_b32_e32 v136, v136, v200, vcc
	v_add_u32_e32 v200, 0xffffffa0, v199
	v_cmp_gt_u32_e64 s[26:27], s76, v200
	v_max3_f32 v198, v198, v140, v141
	v_max3_f32 v198, v198, v142, v143
	v_cndmask_b32_e64 v200, v137, v244, s[26:27]
	v_cndmask_b32_e32 v137, v137, v200, vcc
	v_add_u32_e32 v200, 0xffffffa1, v199
	v_cmp_gt_u32_e64 s[28:29], s76, v200
	v_max3_f32 v198, v198, v136, v137
	s_nop 0
	v_cndmask_b32_e64 v200, v138, v244, s[28:29]
	v_cndmask_b32_e32 v138, v138, v200, vcc
	v_add_u32_e32 v200, 0xffffffa2, v199
	v_cmp_gt_u32_e64 s[30:31], s76, v200
	s_nop 1
	v_cndmask_b32_e64 v200, v139, v244, s[30:31]
	v_cndmask_b32_e32 v139, v139, v200, vcc
	v_add_u32_e32 v200, 0xffffffaf, v199
	v_cmp_gt_u32_e64 s[34:35], s76, v200
	v_max3_f32 v198, v198, v138, v139
	s_nop 0
	v_cndmask_b32_e64 v200, v132, v244, s[34:35]
	v_cndmask_b32_e32 v132, v132, v200, vcc
	v_add_u32_e32 v200, 0xffffffb0, v199
	v_cmp_gt_u32_e64 s[36:37], s76, v200
	s_nop 1
	v_cndmask_b32_e64 v200, v133, v244, s[36:37]
	v_cndmask_b32_e32 v133, v133, v200, vcc
	v_add_u32_e32 v200, 0xffffffb1, v199
	v_cmp_gt_u32_e64 s[38:39], s76, v200
	v_max3_f32 v198, v198, v132, v133
	s_nop 0
	v_cndmask_b32_e64 v200, v134, v244, s[38:39]
	v_cndmask_b32_e32 v134, v134, v200, vcc
	v_add_u32_e32 v200, 0xffffffb2, v199
	v_cmp_gt_u32_e64 s[40:41], s76, v200
	s_nop 1
	v_cndmask_b32_e64 v200, v135, v244, s[40:41]
	v_cndmask_b32_e32 v135, v135, v200, vcc
	v_add_u32_e32 v200, 0xffffffbf, v199
	v_cmp_gt_u32_e64 s[42:43], s76, v200
	v_max3_f32 v198, v198, v134, v135
	s_nop 0
	v_cndmask_b32_e64 v200, v124, v244, s[42:43]
	v_cndmask_b32_e64 v124, v124, v200, s[12:13]
	v_subrev_u32_e32 v200, 64, v199
	v_cmp_gt_u32_e64 s[44:45], s76, v200
	s_nop 1
	v_cndmask_b32_e64 v200, v125, v244, s[44:45]
	v_cndmask_b32_e64 v125, v125, v200, s[12:13]
	v_subrev_u32_e32 v200, 63, v199
	v_cmp_gt_u32_e64 s[46:47], s76, v200
	v_max3_f32 v198, v198, v124, v125
	s_nop 0
	v_cndmask_b32_e64 v200, v126, v244, s[46:47]
	v_cndmask_b32_e64 v126, v126, v200, s[12:13]
	v_subrev_u32_e32 v200, 62, v199
	v_cmp_gt_u32_e64 s[48:49], s76, v200
	s_nop 1
	v_cndmask_b32_e64 v200, v127, v244, s[48:49]
	v_cndmask_b32_e64 v127, v127, v200, s[12:13]
	v_subrev_u32_e32 v200, 49, v199
	v_cmp_gt_u32_e64 s[50:51], s76, v200
	v_max3_f32 v198, v198, v126, v127
	s_nop 0
	v_cndmask_b32_e64 v200, v120, v244, s[50:51]
	v_cndmask_b32_e64 v120, v120, v200, s[12:13]
	v_subrev_u32_e32 v200, 48, v199
	v_cmp_gt_u32_e64 s[52:53], s76, v200
	s_nop 1
	v_cndmask_b32_e64 v200, v121, v244, s[52:53]
	v_cndmask_b32_e64 v121, v121, v200, s[12:13]
	v_subrev_u32_e32 v200, 47, v199
	v_cmp_gt_u32_e64 s[54:55], s76, v200
	v_max3_f32 v198, v198, v120, v121
	s_nop 0
	v_cndmask_b32_e64 v200, v122, v244, s[54:55]
	v_cndmask_b32_e64 v122, v122, v200, s[12:13]
	v_subrev_u32_e32 v200, 46, v199
	v_cmp_gt_u32_e64 s[56:57], s76, v200
	s_nop 1
	v_cndmask_b32_e64 v200, v123, v244, s[56:57]
	v_cndmask_b32_e64 v123, v123, v200, s[12:13]
	v_subrev_u32_e32 v200, 33, v199
	v_cmp_gt_u32_e64 s[58:59], s76, v200
	v_max3_f32 v198, v198, v122, v123
	s_nop 0
	v_cndmask_b32_e64 v200, v116, v244, s[58:59]
	v_cndmask_b32_e64 v116, v116, v200, s[12:13]
	v_subrev_u32_e32 v200, 32, v199
	v_cmp_gt_u32_e64 s[60:61], s76, v200
	s_nop 1
	v_cndmask_b32_e64 v200, v117, v244, s[60:61]
	v_cndmask_b32_e64 v117, v117, v200, s[12:13]
	v_subrev_u32_e32 v200, 31, v199
	v_cmp_gt_u32_e64 s[62:63], s76, v200
	v_max3_f32 v198, v198, v116, v117
	s_nop 0
	v_cndmask_b32_e64 v200, v118, v244, s[62:63]
	v_cndmask_b32_e64 v118, v118, v200, s[12:13]
	v_subrev_u32_e32 v200, 30, v199
	v_cmp_gt_u32_e64 s[64:65], s76, v200
	s_nop 1
	v_cndmask_b32_e64 v200, v119, v244, s[64:65]
	v_cndmask_b32_e64 v119, v119, v200, s[12:13]
	v_subrev_u32_e32 v200, 17, v199
	v_cmp_lt_u32_e64 s[66:67], s68, v200
	v_max3_f32 v198, v198, v118, v119
	s_nop 0
	v_cndmask_b32_e64 v200, v244, v112, s[66:67]
	v_cndmask_b32_e64 v112, v112, v200, s[12:13]
	v_add_u32_e32 v200, -16, v199
	v_cmp_lt_u32_e64 s[66:67], s68, v200
	s_nop 1
	v_cndmask_b32_e64 v200, v244, v113, s[66:67]
	v_cndmask_b32_e64 v113, v113, v200, s[12:13]
	v_add_u32_e32 v200, -15, v199
	v_cmp_lt_u32_e64 s[66:67], s68, v200
	v_max3_f32 v198, v198, v112, v113
	s_nop 0
	v_cndmask_b32_e64 v200, v244, v114, s[66:67]
	v_cndmask_b32_e64 v201, v114, v200, s[12:13]
	v_add_u32_e32 v114, -14, v199
	v_cmp_lt_u32_e64 s[66:67], s68, v114
	s_nop 1
	v_cndmask_b32_e64 v114, v244, v115, s[66:67]
	v_cndmask_b32_e64 v115, v115, v114, s[12:13]
	v_max3_f32 v114, v198, v201, v115
	ds_bpermute_b32 v198, v161, v114
	s_waitcnt lgkmcnt(0)
	v_max_f32_e32 v198, v198, v198
	v_max_f32_e32 v114, v114, v198
	ds_bpermute_b32 v198, v163, v114
	s_waitcnt lgkmcnt(0)
	v_max3_f32 v245, v196, v114, v198
	v_sub_f32_e32 v114, v196, v245
	v_mul_f32_e32 v205, 0xbe38aa3b, v245
	v_mul_f32_e32 v203, 0x3e38aa3b, v114
	v_fmamk_f32 v114, v128, 0x3e38aa3b, v205
	v_exp_f32_e32 v228, v114
	v_fmamk_f32 v114, v129, 0x3e38aa3b, v205
	v_exp_f32_e32 v226, v114
	v_fmamk_f32 v114, v130, 0x3e38aa3b, v205
	v_exp_f32_e32 v224, v114
	v_fmamk_f32 v114, v131, 0x3e38aa3b, v205
	v_exp_f32_e32 v222, v114
	v_fmamk_f32 v114, v140, 0x3e38aa3b, v205
	v_exp_f32_e32 v220, v114
	v_fmamk_f32 v114, v141, 0x3e38aa3b, v205
	v_exp_f32_e32 v218, v114
	v_fmamk_f32 v114, v142, 0x3e38aa3b, v205
	v_exp_f32_e32 v216, v114
	v_fmamk_f32 v114, v143, 0x3e38aa3b, v205
	v_exp_f32_e32 v214, v114
	v_fmamk_f32 v114, v136, 0x3e38aa3b, v205
	v_exp_f32_e32 v212, v114
	v_fmamk_f32 v114, v137, 0x3e38aa3b, v205
	v_exp_f32_e32 v210, v114
	v_fmamk_f32 v114, v138, 0x3e38aa3b, v205
	v_exp_f32_e32 v208, v114
	v_fmamk_f32 v114, v139, 0x3e38aa3b, v205
	v_exp_f32_e32 v206, v114
	v_fmamk_f32 v114, v132, 0x3e38aa3b, v205
	v_exp_f32_e32 v204, v114
	v_fmamk_f32 v114, v133, 0x3e38aa3b, v205
	v_exp_f32_e32 v202, v114
	v_fmamk_f32 v114, v134, 0x3e38aa3b, v205
	v_exp_f32_e32 v200, v114
	v_fmamk_f32 v114, v135, 0x3e38aa3b, v205
	v_exp_f32_e32 v198, v114
	v_fmamk_f32 v114, v124, 0x3e38aa3b, v205
	v_exp_f32_e32 v196, v114
	v_fmamk_f32 v114, v125, 0x3e38aa3b, v205
	v_exp_f32_e32 v142, v114
	v_fmamk_f32 v114, v126, 0x3e38aa3b, v205
	v_exp_f32_e32 v140, v114
	v_fmamk_f32 v114, v127, 0x3e38aa3b, v205
	v_exp_f32_e32 v138, v114
	v_fmamk_f32 v114, v120, 0x3e38aa3b, v205
	v_exp_f32_e32 v136, v114
	v_fmamk_f32 v114, v121, 0x3e38aa3b, v205
	v_exp_f32_e32 v134, v114
	v_fmamk_f32 v114, v122, 0x3e38aa3b, v205
	v_exp_f32_e32 v132, v114
	v_fmamk_f32 v114, v123, 0x3e38aa3b, v205
	v_exp_f32_e32 v130, v114
	v_fmamk_f32 v114, v116, 0x3e38aa3b, v205
	v_exp_f32_e32 v128, v114
	v_fmamk_f32 v114, v117, 0x3e38aa3b, v205
	v_exp_f32_e32 v126, v114
	v_fmamk_f32 v114, v118, 0x3e38aa3b, v205
	v_fmamk_f32 v112, v112, 0x3e38aa3b, v205
	v_exp_f32_e32 v122, v114
	v_fmamk_f32 v114, v119, 0x3e38aa3b, v205
	v_exp_f32_e32 v116, v112
	v_fmamk_f32 v112, v113, 0x3e38aa3b, v205
	v_exp_f32_e32 v118, v114
	v_exp_f32_e32 v114, v112
	v_exp_f32_e32 v112, v203
	v_fmamk_f32 v113, v201, 0x3e38aa3b, v205
	v_exp_f32_e32 v124, v113
	v_fmac_f32_e32 v205, 0x3e38aa3b, v115
	v_pk_mul_f32 v[78:79], v[78:79], v[112:113] op_sel_hi:[1,0]
	v_pk_mul_f32 v[76:77], v[76:77], v[112:113] op_sel_hi:[1,0]
	v_pk_mul_f32 v[74:75], v[74:75], v[112:113] op_sel_hi:[1,0]
	v_pk_mul_f32 v[72:73], v[72:73], v[112:113] op_sel_hi:[1,0]
	v_pk_mul_f32 v[58:59], v[58:59], v[112:113] op_sel_hi:[1,0]
	v_pk_mul_f32 v[56:57], v[56:57], v[112:113] op_sel_hi:[1,0]
	v_pk_mul_f32 v[34:35], v[34:35], v[112:113] op_sel_hi:[1,0]
	v_pk_mul_f32 v[32:33], v[32:33], v[112:113] op_sel_hi:[1,0]
	v_add_u32_e32 v113, 0xffffff6f, v199
	v_cmp_lt_u32_e64 s[66:67], s68, v113
	v_add_u32_e32 v115, 0xffffff71, v199
	v_exp_f32_e32 v120, v205
	v_cndmask_b32_e64 v113, v244, v80, s[66:67]
	v_cndmask_b32_e32 v80, v80, v113, vcc
	v_add_u32_e32 v113, 0xffffff70, v199
	v_cmp_lt_u32_e64 s[66:67], s68, v113
	s_nop 1
	v_cndmask_b32_e64 v113, v244, v81, s[66:67]
	v_cmp_lt_u32_e64 s[66:67], s68, v115
	v_cndmask_b32_e32 v113, v81, v113, vcc
	v_max3_f32 v81, v80, s77, v113
	v_cndmask_b32_e64 v115, v244, v82, s[66:67]
	v_cndmask_b32_e32 v115, v82, v115, vcc
	v_add_u32_e32 v82, 0xffffff72, v199
	v_cmp_lt_u32_e64 s[66:67], s68, v82
	s_nop 1
	v_cndmask_b32_e64 v82, v244, v83, s[66:67]
	v_cndmask_b32_e32 v117, v83, v82, vcc
	v_cndmask_b32_e64 v82, v96, v244, s[6:7]
	v_cndmask_b32_e32 v96, v96, v82, vcc
	v_cndmask_b32_e64 v82, v97, v244, s[8:9]
	v_cndmask_b32_e32 v97, v97, v82, vcc
	v_cndmask_b32_e64 v82, v98, v244, s[10:11]
	v_cndmask_b32_e32 v98, v98, v82, vcc
	v_cndmask_b32_e64 v82, v99, v244, s[14:15]
	v_cndmask_b32_e32 v99, v99, v82, vcc
	v_cndmask_b32_e64 v82, v104, v244, s[16:17]
	v_cndmask_b32_e32 v104, v104, v82, vcc
	v_cndmask_b32_e64 v82, v105, v244, s[18:19]
	v_cndmask_b32_e32 v105, v105, v82, vcc
	v_cndmask_b32_e64 v82, v106, v244, s[20:21]
	v_cndmask_b32_e32 v106, v106, v82, vcc
	v_cndmask_b32_e64 v82, v107, v244, s[22:23]
	v_cndmask_b32_e32 v107, v107, v82, vcc
	v_cndmask_b32_e64 v82, v108, v244, s[24:25]
	v_cndmask_b32_e32 v108, v108, v82, vcc
	v_cndmask_b32_e64 v82, v109, v244, s[26:27]
	v_cndmask_b32_e32 v109, v109, v82, vcc
	v_cndmask_b32_e64 v82, v110, v244, s[28:29]
	v_cndmask_b32_e32 v110, v110, v82, vcc
	v_cndmask_b32_e64 v82, v111, v244, s[30:31]
	v_cndmask_b32_e32 v111, v111, v82, vcc
	v_cndmask_b32_e64 v82, v84, v244, s[34:35]
	v_cndmask_b32_e64 v119, v84, v82, s[12:13]
	v_cndmask_b32_e64 v82, v85, v244, s[36:37]
	v_cndmask_b32_e64 v121, v85, v82, s[12:13]
	v_cndmask_b32_e64 v82, v86, v244, s[38:39]
	v_max3_f32 v81, v81, v115, v117
	v_cndmask_b32_e64 v123, v86, v82, s[12:13]
	v_cndmask_b32_e64 v82, v87, v244, s[40:41]
	v_max3_f32 v81, v81, v96, v97
	v_cndmask_b32_e64 v125, v87, v82, s[12:13]
	v_cndmask_b32_e64 v82, v88, v244, s[42:43]
	v_max3_f32 v81, v81, v98, v99
	v_cndmask_b32_e64 v127, v88, v82, s[12:13]
	v_cndmask_b32_e64 v82, v89, v244, s[44:45]
	v_max3_f32 v81, v81, v104, v105
	v_cndmask_b32_e64 v129, v89, v82, s[12:13]
	v_cndmask_b32_e64 v82, v90, v244, s[46:47]
	v_max3_f32 v81, v81, v106, v107
	v_cndmask_b32_e64 v90, v90, v82, s[12:13]
	v_cndmask_b32_e64 v82, v91, v244, s[48:49]
	v_max3_f32 v81, v81, v108, v109
	v_cndmask_b32_e64 v91, v91, v82, s[12:13]
	v_cndmask_b32_e64 v82, v92, v244, s[50:51]
	v_max3_f32 v81, v81, v110, v111
	v_cndmask_b32_e64 v92, v92, v82, s[12:13]
	v_cndmask_b32_e64 v82, v93, v244, s[52:53]
	v_max3_f32 v81, v81, v119, v121
	v_cndmask_b32_e64 v93, v93, v82, s[12:13]
	v_cndmask_b32_e64 v82, v94, v244, s[54:55]
	v_max3_f32 v81, v81, v123, v125
	v_cndmask_b32_e64 v94, v94, v82, s[12:13]
	v_cndmask_b32_e64 v82, v95, v244, s[56:57]
	v_max3_f32 v81, v81, v127, v129
	v_cndmask_b32_e64 v95, v95, v82, s[12:13]
	v_cndmask_b32_e64 v82, v100, v244, s[58:59]
	v_max3_f32 v81, v81, v90, v91
	v_cndmask_b32_e64 v100, v100, v82, s[12:13]
	v_cndmask_b32_e64 v82, v101, v244, s[60:61]
	v_max3_f32 v81, v81, v92, v93
	v_cndmask_b32_e64 v101, v101, v82, s[12:13]
	v_cndmask_b32_e64 v82, v102, v244, s[62:63]
	v_max3_f32 v81, v81, v94, v95
	v_cndmask_b32_e64 v102, v102, v82, s[12:13]
	v_cndmask_b32_e64 v82, v103, v244, s[64:65]
	v_max3_f32 v81, v81, v100, v101
	v_cndmask_b32_e64 v103, v103, v82, s[12:13]
	s_branch .Lattna_join
.Lattna_fast:
	s_cmp_lt_i32 s4, s33
	s_cselect_b64 s[10:11], -1, 0
	s_and_b64 vcc, s[88:89], s[10:11]
	s_cmp_lt_i32 s8, s33
	s_cselect_b64 s[12:13], -1, 0
	s_and_b64 s[12:13], s[88:89], s[12:13]
	v_max3_f32 v198, v128, s77, v129
	v_max3_f32 v198, v198, v130, v131
	v_max3_f32 v198, v198, v140, v141
	v_max3_f32 v198, v198, v142, v143
	v_max3_f32 v198, v198, v136, v137
	v_max3_f32 v198, v198, v138, v139
	v_max3_f32 v198, v198, v132, v133
	v_max3_f32 v198, v198, v134, v135
	v_max3_f32 v198, v198, v124, v125
	v_max3_f32 v198, v198, v126, v127
	v_max3_f32 v198, v198, v120, v121
	v_max3_f32 v198, v198, v122, v123
	v_max3_f32 v198, v198, v116, v117
	v_max3_f32 v198, v198, v118, v119
	v_max3_f32 v198, v198, v112, v113
	v_mov_b32_e32 v201, v114
	v_max3_f32 v114, v198, v201, v115
	ds_bpermute_b32 v198, v161, v114
	s_waitcnt lgkmcnt(0)
	v_max_f32_e32 v198, v198, v198
	v_max_f32_e32 v114, v114, v198
	ds_bpermute_b32 v198, v163, v114
	s_waitcnt lgkmcnt(0)
	v_max3_f32 v245, v196, v114, v198
	v_sub_f32_e32 v114, v196, v245
	v_mul_f32_e32 v205, 0xbe38aa3b, v245
	v_mul_f32_e32 v203, 0x3e38aa3b, v114
	v_fmamk_f32 v114, v128, 0x3e38aa3b, v205
	v_exp_f32_e32 v228, v114
	v_fmamk_f32 v114, v129, 0x3e38aa3b, v205
	v_exp_f32_e32 v226, v114
	v_fmamk_f32 v114, v130, 0x3e38aa3b, v205
	v_exp_f32_e32 v224, v114
	v_fmamk_f32 v114, v131, 0x3e38aa3b, v205
	v_exp_f32_e32 v222, v114
	v_fmamk_f32 v114, v140, 0x3e38aa3b, v205
	v_exp_f32_e32 v220, v114
	v_fmamk_f32 v114, v141, 0x3e38aa3b, v205
	v_exp_f32_e32 v218, v114
	v_fmamk_f32 v114, v142, 0x3e38aa3b, v205
	v_exp_f32_e32 v216, v114
	v_fmamk_f32 v114, v143, 0x3e38aa3b, v205
	v_exp_f32_e32 v214, v114
	v_fmamk_f32 v114, v136, 0x3e38aa3b, v205
	v_exp_f32_e32 v212, v114
	v_fmamk_f32 v114, v137, 0x3e38aa3b, v205
	v_exp_f32_e32 v210, v114
	v_fmamk_f32 v114, v138, 0x3e38aa3b, v205
	v_exp_f32_e32 v208, v114
	v_fmamk_f32 v114, v139, 0x3e38aa3b, v205
	v_exp_f32_e32 v206, v114
	v_fmamk_f32 v114, v132, 0x3e38aa3b, v205
	v_exp_f32_e32 v204, v114
	v_fmamk_f32 v114, v133, 0x3e38aa3b, v205
	v_exp_f32_e32 v202, v114
	v_fmamk_f32 v114, v134, 0x3e38aa3b, v205
	v_exp_f32_e32 v200, v114
	v_fmamk_f32 v114, v135, 0x3e38aa3b, v205
	v_exp_f32_e32 v198, v114
	v_fmamk_f32 v114, v124, 0x3e38aa3b, v205
	v_exp_f32_e32 v196, v114
	v_fmamk_f32 v114, v125, 0x3e38aa3b, v205
	v_exp_f32_e32 v142, v114
	v_fmamk_f32 v114, v126, 0x3e38aa3b, v205
	v_exp_f32_e32 v140, v114
	v_fmamk_f32 v114, v127, 0x3e38aa3b, v205
	v_exp_f32_e32 v138, v114
	v_fmamk_f32 v114, v120, 0x3e38aa3b, v205
	v_exp_f32_e32 v136, v114
	v_fmamk_f32 v114, v121, 0x3e38aa3b, v205
	v_exp_f32_e32 v134, v114
	v_fmamk_f32 v114, v122, 0x3e38aa3b, v205
	v_exp_f32_e32 v132, v114
	v_fmamk_f32 v114, v123, 0x3e38aa3b, v205
	v_exp_f32_e32 v130, v114
	v_fmamk_f32 v114, v116, 0x3e38aa3b, v205
	v_exp_f32_e32 v128, v114
	v_fmamk_f32 v114, v117, 0x3e38aa3b, v205
	v_exp_f32_e32 v126, v114
	v_fmamk_f32 v114, v118, 0x3e38aa3b, v205
	v_fmamk_f32 v112, v112, 0x3e38aa3b, v205
	v_exp_f32_e32 v122, v114
	v_fmamk_f32 v114, v119, 0x3e38aa3b, v205
	v_exp_f32_e32 v116, v112
	v_fmamk_f32 v112, v113, 0x3e38aa3b, v205
	v_exp_f32_e32 v118, v114
	v_exp_f32_e32 v114, v112
	v_exp_f32_e32 v112, v203
	v_fmamk_f32 v113, v201, 0x3e38aa3b, v205
	v_exp_f32_e32 v124, v113
	v_fmac_f32_e32 v205, 0x3e38aa3b, v115
	v_pk_mul_f32 v[78:79], v[78:79], v[112:113] op_sel_hi:[1,0]
	v_pk_mul_f32 v[76:77], v[76:77], v[112:113] op_sel_hi:[1,0]
	v_pk_mul_f32 v[74:75], v[74:75], v[112:113] op_sel_hi:[1,0]
	v_pk_mul_f32 v[72:73], v[72:73], v[112:113] op_sel_hi:[1,0]
	v_pk_mul_f32 v[58:59], v[58:59], v[112:113] op_sel_hi:[1,0]
	v_pk_mul_f32 v[56:57], v[56:57], v[112:113] op_sel_hi:[1,0]
	v_pk_mul_f32 v[34:35], v[34:35], v[112:113] op_sel_hi:[1,0]
	v_pk_mul_f32 v[32:33], v[32:33], v[112:113] op_sel_hi:[1,0]
	v_exp_f32_e32 v120, v205
	v_mov_b32_e32 v113, v81
	v_max3_f32 v81, v80, s77, v113
	v_mov_b32_e32 v115, v82
	v_mov_b32_e32 v117, v83
	v_mov_b32_e32 v119, v84
	v_mov_b32_e32 v121, v85
	v_max3_f32 v81, v81, v115, v117
	v_mov_b32_e32 v123, v86
	v_max3_f32 v81, v81, v96, v97
	v_mov_b32_e32 v125, v87
	v_max3_f32 v81, v81, v98, v99
	v_mov_b32_e32 v127, v88
	v_max3_f32 v81, v81, v104, v105
	v_mov_b32_e32 v129, v89
	v_max3_f32 v81, v81, v106, v107
	v_max3_f32 v81, v81, v108, v109
	v_max3_f32 v81, v81, v110, v111
	v_max3_f32 v81, v81, v119, v121
	v_max3_f32 v81, v81, v123, v125
	v_max3_f32 v81, v81, v127, v129
	v_max3_f32 v81, v81, v90, v91
	v_max3_f32 v81, v81, v92, v93
	v_max3_f32 v81, v81, v94, v95
	v_max3_f32 v81, v81, v100, v101
.Lattna_join:
	v_max3_f32 v81, v81, v102, v103
	ds_bpermute_b32 v86, v161, v81
	v_cvt_pk_bf16_f32 v82, v228, v226
	v_cvt_pk_bf16_f32 v83, v224, v222
	v_cvt_pk_bf16_f32 v84, v220, v218
	v_cvt_pk_bf16_f32 v85, v216, v214
	s_waitcnt lgkmcnt(0)
	v_max_f32_e32 v86, v86, v86
	v_max_f32_e32 v81, v81, v86
	ds_bpermute_b32 v131, v163, v81
	v_cvt_pk_bf16_f32 v86, v212, v210
	v_cvt_pk_bf16_f32 v87, v208, v206
	v_cvt_pk_bf16_f32 v88, v204, v202
	v_cvt_pk_bf16_f32 v89, v200, v198
	s_waitcnt lgkmcnt(0)
	v_max3_f32 v81, v197, v81, v131
	v_mul_f32_e32 v247, 0xbe38aa3b, v81
	v_fmamk_f32 v80, v80, 0x3e38aa3b, v247
	v_exp_f32_e32 v229, v80
	v_fmamk_f32 v80, v113, 0x3e38aa3b, v247
	v_exp_f32_e32 v227, v80
	v_fmamk_f32 v80, v115, 0x3e38aa3b, v247
	v_exp_f32_e32 v225, v80
	v_fmamk_f32 v80, v117, 0x3e38aa3b, v247
	v_exp_f32_e32 v223, v80
	v_fmamk_f32 v80, v96, 0x3e38aa3b, v247
	v_exp_f32_e32 v221, v80
	v_fmamk_f32 v80, v97, 0x3e38aa3b, v247
	v_exp_f32_e32 v219, v80
	v_fmamk_f32 v80, v98, 0x3e38aa3b, v247
	v_exp_f32_e32 v217, v80
	v_fmamk_f32 v80, v99, 0x3e38aa3b, v247
	v_exp_f32_e32 v215, v80
	v_fmamk_f32 v80, v104, 0x3e38aa3b, v247
	v_exp_f32_e32 v213, v80
	v_fmamk_f32 v80, v105, 0x3e38aa3b, v247
	v_exp_f32_e32 v211, v80
	v_fmamk_f32 v80, v106, 0x3e38aa3b, v247
	v_exp_f32_e32 v209, v80
	v_fmamk_f32 v80, v107, 0x3e38aa3b, v247
	v_exp_f32_e32 v207, v80
	v_fmamk_f32 v80, v108, 0x3e38aa3b, v247
	v_exp_f32_e32 v205, v80
	v_fmamk_f32 v80, v109, 0x3e38aa3b, v247
	v_exp_f32_e32 v203, v80
	v_fmamk_f32 v80, v110, 0x3e38aa3b, v247
	v_exp_f32_e32 v201, v80
	v_fmamk_f32 v80, v111, 0x3e38aa3b, v247
	v_exp_f32_e32 v199, v80
	v_fmamk_f32 v80, v119, 0x3e38aa3b, v247
	v_sub_f32_e32 v131, v197, v81
	v_exp_f32_e32 v197, v80
	v_fmamk_f32 v80, v121, 0x3e38aa3b, v247
	v_exp_f32_e32 v143, v80
	v_fmamk_f32 v80, v123, 0x3e38aa3b, v247
	v_exp_f32_e32 v141, v80
	v_fmamk_f32 v80, v125, 0x3e38aa3b, v247
	v_exp_f32_e32 v139, v80
	v_fmamk_f32 v80, v127, 0x3e38aa3b, v247
	v_exp_f32_e32 v137, v80
	v_fmamk_f32 v80, v129, 0x3e38aa3b, v247
	v_exp_f32_e32 v135, v80
	v_fmamk_f32 v80, v90, 0x3e38aa3b, v247
	v_exp_f32_e32 v133, v80
	v_fmamk_f32 v80, v91, 0x3e38aa3b, v247
	v_mul_f32_e32 v246, 0x3e38aa3b, v131
	v_exp_f32_e32 v131, v80
	v_fmamk_f32 v80, v92, 0x3e38aa3b, v247
	v_exp_f32_e32 v129, v80
	v_fmamk_f32 v80, v93, 0x3e38aa3b, v247
	v_exp_f32_e32 v127, v80
	v_fmamk_f32 v80, v94, 0x3e38aa3b, v247
	v_exp_f32_e32 v123, v80
	v_fmamk_f32 v80, v95, 0x3e38aa3b, v247
	v_exp_f32_e32 v119, v80
	v_fmamk_f32 v80, v100, 0x3e38aa3b, v247
	v_exp_f32_e32 v117, v80
	v_fmamk_f32 v80, v101, 0x3e38aa3b, v247
	v_exp_f32_e32 v115, v80
	v_fmamk_f32 v90, v102, 0x3e38aa3b, v247
	v_exp_f32_e32 v80, v246
	v_fmac_f32_e32 v247, 0x3e38aa3b, v103
	v_exp_f32_e32 v125, v90
	v_exp_f32_e32 v121, v247
	v_pk_mul_f32 v[14:15], v[14:15], v[80:81] op_sel_hi:[1,0]
	v_pk_mul_f32 v[12:13], v[12:13], v[80:81] op_sel_hi:[1,0]
	v_pk_mul_f32 v[10:11], v[10:11], v[80:81] op_sel_hi:[1,0]
	v_pk_mul_f32 v[8:9], v[8:9], v[80:81] op_sel_hi:[1,0]
	v_pk_mul_f32 v[6:7], v[6:7], v[80:81] op_sel_hi:[1,0]
	v_pk_mul_f32 v[4:5], v[4:5], v[80:81] op_sel_hi:[1,0]
	v_pk_mul_f32 v[2:3], v[2:3], v[80:81] op_sel_hi:[1,0]
	v_pk_mul_f32 v[0:1], v[0:1], v[80:81] op_sel_hi:[1,0]
	v_cvt_pk_bf16_f32 v90, v229, v227
	v_cvt_pk_bf16_f32 v91, v225, v223
	v_cvt_pk_bf16_f32 v92, v221, v219
	v_cvt_pk_bf16_f32 v93, v217, v215
	v_cvt_pk_bf16_f32 v94, v213, v211
	v_cvt_pk_bf16_f32 v95, v209, v207
	v_cvt_pk_bf16_f32 v96, v205, v203
	v_cvt_pk_bf16_f32 v97, v201, v199
	s_setprio 1
	ds_read_b128 v[98:101], v169 offset:10240
	ds_read_b128 v[102:105], v169 offset:10304
	s_andn2_b64 vcc, exec, s[94:95]
	s_waitcnt lgkmcnt(1)
	v_mfma_f32_16x16x32_bf16 v[76:79], v[98:101], v[82:85], v[76:79]
	v_mfma_f32_16x16x32_bf16 v[12:15], v[98:101], v[90:93], v[12:15]
	s_waitcnt lgkmcnt(0)
	v_mfma_f32_16x16x32_bf16 v[76:79], v[102:105], v[86:89], v[76:79]
	v_mfma_f32_16x16x32_bf16 v[12:15], v[102:105], v[94:97], v[12:15]
	ds_read_b128 v[98:101], v169 offset:12800
	ds_read_b128 v[102:105], v169 offset:12864
	s_waitcnt lgkmcnt(1)
	v_mfma_f32_16x16x32_bf16 v[72:75], v[98:101], v[82:85], v[72:75]
	v_mfma_f32_16x16x32_bf16 v[8:11], v[98:101], v[90:93], v[8:11]
	s_waitcnt lgkmcnt(0)
	v_mfma_f32_16x16x32_bf16 v[72:75], v[102:105], v[86:89], v[72:75]
	v_mfma_f32_16x16x32_bf16 v[8:11], v[102:105], v[94:97], v[8:11]
	ds_read_b128 v[98:101], v169 offset:15360
	ds_read_b128 v[102:105], v169 offset:15424
	s_waitcnt lgkmcnt(1)
	v_mfma_f32_16x16x32_bf16 v[56:59], v[98:101], v[82:85], v[56:59]
	v_mfma_f32_16x16x32_bf16 v[4:7], v[98:101], v[90:93], v[4:7]
	s_waitcnt lgkmcnt(0)
	v_mfma_f32_16x16x32_bf16 v[56:59], v[102:105], v[86:89], v[56:59]
	v_mfma_f32_16x16x32_bf16 v[4:7], v[102:105], v[94:97], v[4:7]
	ds_read_b128 v[98:101], v169 offset:17920
	ds_read_b128 v[102:105], v169 offset:17984
	s_waitcnt lgkmcnt(1)
	v_mfma_f32_16x16x32_bf16 v[32:35], v[98:101], v[82:85], v[32:35]
	v_mfma_f32_16x16x32_bf16 v[0:3], v[98:101], v[90:93], v[0:3]
	s_waitcnt lgkmcnt(0)
	v_mfma_f32_16x16x32_bf16 v[32:35], v[102:105], v[86:89], v[32:35]
	v_mfma_f32_16x16x32_bf16 v[0:3], v[102:105], v[94:97], v[0:3]
	s_cbranch_vccnz .LBB0_389
	ds_read_b128 v[82:85], v169 offset:30720
	ds_read_b128 v[98:101], v169 offset:30784
	v_cvt_pk_bf16_f32 v90, v196, v142
	v_cvt_pk_bf16_f32 v91, v140, v138
	v_cvt_pk_bf16_f32 v92, v136, v134
	v_cvt_pk_bf16_f32 v93, v132, v130
	v_cvt_pk_bf16_f32 v94, v197, v143
	v_cvt_pk_bf16_f32 v95, v141, v139
	v_cvt_pk_bf16_f32 v96, v137, v135
	v_cvt_pk_bf16_f32 v97, v133, v131
	s_waitcnt lgkmcnt(1)
	v_mfma_f32_16x16x32_bf16 v[76:79], v[82:85], v[90:93], v[76:79]
	v_cvt_pk_bf16_f32 v86, v128, v126
	v_cvt_pk_bf16_f32 v87, v122, v118
	v_cvt_pk_bf16_f32 v88, v116, v114
	v_mfma_f32_16x16x32_bf16 v[12:15], v[82:85], v[94:97], v[12:15]
	v_cvt_pk_bf16_f32 v89, v124, v120
	v_cvt_pk_bf16_f32 v82, v129, v127
	v_cvt_pk_bf16_f32 v83, v123, v119
	v_cvt_pk_bf16_f32 v84, v117, v115
	v_cvt_pk_bf16_f32 v85, v125, v121
	s_waitcnt lgkmcnt(0)
	v_mfma_f32_16x16x32_bf16 v[76:79], v[98:101], v[86:89], v[76:79]
	v_mfma_f32_16x16x32_bf16 v[12:15], v[98:101], v[82:85], v[12:15]
	ds_read_b128 v[98:101], v169 offset:33280
	ds_read_b128 v[102:105], v169 offset:33344
	s_waitcnt lgkmcnt(1)
	v_mfma_f32_16x16x32_bf16 v[72:75], v[98:101], v[90:93], v[72:75]
	v_mfma_f32_16x16x32_bf16 v[8:11], v[98:101], v[94:97], v[8:11]
	s_waitcnt lgkmcnt(0)
	v_mfma_f32_16x16x32_bf16 v[72:75], v[102:105], v[86:89], v[72:75]
	v_mfma_f32_16x16x32_bf16 v[8:11], v[102:105], v[82:85], v[8:11]
	ds_read_b128 v[98:101], v169 offset:35840
	ds_read_b128 v[102:105], v169 offset:35904
	s_waitcnt lgkmcnt(1)
	v_mfma_f32_16x16x32_bf16 v[56:59], v[98:101], v[90:93], v[56:59]
	v_mfma_f32_16x16x32_bf16 v[4:7], v[98:101], v[94:97], v[4:7]
	s_waitcnt lgkmcnt(0)
	v_mfma_f32_16x16x32_bf16 v[56:59], v[102:105], v[86:89], v[56:59]
	v_mfma_f32_16x16x32_bf16 v[4:7], v[102:105], v[82:85], v[4:7]
	ds_read_b128 v[98:101], v169 offset:38400
	ds_read_b128 v[102:105], v169 offset:38464
	s_waitcnt lgkmcnt(1)
	v_mfma_f32_16x16x32_bf16 v[32:35], v[98:101], v[90:93], v[32:35]
	v_mfma_f32_16x16x32_bf16 v[0:3], v[98:101], v[94:97], v[0:3]
	s_waitcnt lgkmcnt(0)
	v_mfma_f32_16x16x32_bf16 v[32:35], v[102:105], v[86:89], v[32:35]
	v_mfma_f32_16x16x32_bf16 v[0:3], v[102:105], v[82:85], v[0:3]

.LBB0_1270:
	s_setprio 0
	s_cmp_ge_i32 s4, s33
	s_cbranch_scc1 .Lattnb_fast
	s_and_b64 vcc, s[86:87], exec
	s_cbranch_scc0 .Lattnb_fast
	s_cmp_lt_i32 s4, s33
	v_add_u32_e32 v189, s5, v167
	s_cselect_b64 s[12:13], -1, 0
	v_add_u32_e32 v190, 0xffffff81, v189
	s_and_b64 vcc, s[86:87], s[12:13]
	v_cmp_gt_u32_e64 s[12:13], s76, v190
	s_cmp_lt_i32 s10, s33
	s_cselect_b64 s[14:15], -1, 0
	v_cndmask_b32_e64 v190, v130, v223, s[12:13]
	v_cndmask_b32_e32 v130, v130, v190, vcc
	v_add_u32_e32 v190, 0xffffff82, v189
	v_cmp_gt_u32_e64 s[16:17], s76, v190
	s_and_b64 s[14:15], s[86:87], s[14:15]
	v_add_u32_e32 v188, 0xffffff7f, v189
	v_cndmask_b32_e64 v190, v131, v223, s[16:17]
	v_cndmask_b32_e32 v131, v131, v190, vcc
	v_add_u32_e32 v190, 0xffffff8f, v189
	v_cmp_gt_u32_e64 s[18:19], s76, v190
	v_cmp_gt_u32_e64 s[6:7], s76, v188
	s_nop 0
	v_cndmask_b32_e64 v190, v140, v223, s[18:19]
	v_cndmask_b32_e32 v140, v140, v190, vcc
	v_add_u32_e32 v190, 0xffffff90, v189
	v_cmp_gt_u32_e64 s[20:21], s76, v190
	v_cndmask_b32_e64 v188, v128, v223, s[6:7]
	v_cndmask_b32_e32 v128, v128, v188, vcc
	v_cndmask_b32_e64 v190, v141, v223, s[20:21]
	v_cndmask_b32_e32 v141, v141, v190, vcc
	v_add_u32_e32 v190, 0xffffff91, v189
	v_cmp_gt_u32_e64 s[22:23], s76, v190
	v_add_u32_e32 v188, 0xffffff80, v189
	v_cmp_gt_u32_e64 s[10:11], s76, v188
	v_cndmask_b32_e64 v190, v142, v223, s[22:23]
	v_cndmask_b32_e32 v142, v142, v190, vcc
	v_add_u32_e32 v190, 0xffffff92, v189
	v_cmp_gt_u32_e64 s[24:25], s76, v190
	v_cndmask_b32_e64 v188, v129, v223, s[10:11]
	v_cndmask_b32_e32 v129, v129, v188, vcc
	v_cndmask_b32_e64 v190, v143, v223, s[24:25]
	v_cndmask_b32_e32 v143, v143, v190, vcc
	v_add_u32_e32 v190, 0xffffff9f, v189
	v_cmp_gt_u32_e64 s[26:27], s76, v190
	v_max3_f32 v188, v128, s77, v129
	v_max3_f32 v188, v188, v130, v131
	v_cndmask_b32_e64 v190, v136, v223, s[26:27]
	v_cndmask_b32_e32 v136, v136, v190, vcc
	v_add_u32_e32 v190, 0xffffffa0, v189
	v_cmp_gt_u32_e64 s[28:29], s76, v190
	v_max3_f32 v188, v188, v140, v141
	v_max3_f32 v188, v188, v142, v143
	v_cndmask_b32_e64 v190, v137, v223, s[28:29]
	v_cndmask_b32_e32 v137, v137, v190, vcc
	v_add_u32_e32 v190, 0xffffffa1, v189
	v_cmp_gt_u32_e64 s[30:31], s76, v190
	v_max3_f32 v188, v188, v136, v137
	s_nop 0
	v_cndmask_b32_e64 v190, v138, v223, s[30:31]
	v_cndmask_b32_e32 v138, v138, v190, vcc
	v_add_u32_e32 v190, 0xffffffa2, v189
	v_cmp_gt_u32_e64 s[34:35], s76, v190
	s_nop 1
	v_cndmask_b32_e64 v190, v139, v223, s[34:35]
	v_cndmask_b32_e32 v139, v139, v190, vcc
	v_add_u32_e32 v190, 0xffffffaf, v189
	v_cmp_gt_u32_e64 s[36:37], s76, v190
	v_max3_f32 v188, v188, v138, v139
	s_nop 0
	v_cndmask_b32_e64 v190, v132, v223, s[36:37]
	v_cndmask_b32_e32 v132, v132, v190, vcc
	v_add_u32_e32 v190, 0xffffffb0, v189
	v_cmp_gt_u32_e64 s[38:39], s76, v190
	s_nop 1
	v_cndmask_b32_e64 v190, v133, v223, s[38:39]
	v_cndmask_b32_e32 v133, v133, v190, vcc
	v_add_u32_e32 v190, 0xffffffb1, v189
	v_cmp_gt_u32_e64 s[40:41], s76, v190
	v_max3_f32 v188, v188, v132, v133
	s_nop 0
	v_cndmask_b32_e64 v190, v134, v223, s[40:41]
	v_cndmask_b32_e32 v134, v134, v190, vcc
	v_add_u32_e32 v190, 0xffffffb2, v189
	v_cmp_gt_u32_e64 s[42:43], s76, v190
	s_nop 1
	v_cndmask_b32_e64 v190, v135, v223, s[42:43]
	v_cndmask_b32_e32 v135, v135, v190, vcc
	v_add_u32_e32 v190, 0xffffffbf, v189
	v_cmp_gt_u32_e64 s[44:45], s76, v190
	v_max3_f32 v188, v188, v134, v135
	s_nop 0
	v_cndmask_b32_e64 v190, v124, v223, s[44:45]
	v_cndmask_b32_e64 v124, v124, v190, s[14:15]
	v_subrev_u32_e32 v190, 64, v189
	v_cmp_gt_u32_e64 s[46:47], s76, v190
	s_nop 1
	v_cndmask_b32_e64 v190, v125, v223, s[46:47]
	v_cndmask_b32_e64 v125, v125, v190, s[14:15]
	v_subrev_u32_e32 v190, 63, v189
	v_cmp_gt_u32_e64 s[48:49], s76, v190
	v_max3_f32 v188, v188, v124, v125
	s_nop 0
	v_cndmask_b32_e64 v190, v126, v223, s[48:49]
	v_cndmask_b32_e64 v126, v126, v190, s[14:15]
	v_subrev_u32_e32 v190, 62, v189
	v_cmp_gt_u32_e64 s[50:51], s76, v190
	s_nop 1
	v_cndmask_b32_e64 v190, v127, v223, s[50:51]
	v_cndmask_b32_e64 v127, v127, v190, s[14:15]
	v_subrev_u32_e32 v190, 49, v189
	v_cmp_gt_u32_e64 s[52:53], s76, v190
	v_max3_f32 v188, v188, v126, v127
	s_nop 0
	v_cndmask_b32_e64 v190, v120, v223, s[52:53]
	v_cndmask_b32_e64 v120, v120, v190, s[14:15]
	v_subrev_u32_e32 v190, 48, v189
	v_cmp_gt_u32_e64 s[54:55], s76, v190
	s_nop 1
	v_cndmask_b32_e64 v190, v121, v223, s[54:55]
	v_cndmask_b32_e64 v121, v121, v190, s[14:15]
	v_subrev_u32_e32 v190, 47, v189
	v_cmp_gt_u32_e64 s[56:57], s76, v190
	v_max3_f32 v188, v188, v120, v121
	s_nop 0
	v_cndmask_b32_e64 v190, v122, v223, s[56:57]
	v_cndmask_b32_e64 v122, v122, v190, s[14:15]
	v_subrev_u32_e32 v190, 46, v189
	v_cmp_gt_u32_e64 s[58:59], s76, v190
	s_nop 1
	v_cndmask_b32_e64 v190, v123, v223, s[58:59]
	v_cndmask_b32_e64 v123, v123, v190, s[14:15]
	v_subrev_u32_e32 v190, 33, v189
	v_cmp_gt_u32_e64 s[60:61], s76, v190
	v_max3_f32 v188, v188, v122, v123
	s_nop 0
	v_cndmask_b32_e64 v190, v116, v223, s[60:61]
	v_cndmask_b32_e64 v116, v116, v190, s[14:15]
	v_subrev_u32_e32 v190, 32, v189
	v_cmp_gt_u32_e64 s[62:63], s76, v190
	s_nop 1
	v_cndmask_b32_e64 v190, v117, v223, s[62:63]
	v_cndmask_b32_e64 v117, v117, v190, s[14:15]
	v_subrev_u32_e32 v190, 31, v189
	v_cmp_gt_u32_e64 s[64:65], s76, v190
	v_max3_f32 v188, v188, v116, v117
	s_nop 0
	v_cndmask_b32_e64 v190, v118, v223, s[64:65]
	v_cndmask_b32_e64 v118, v118, v190, s[14:15]
	v_subrev_u32_e32 v190, 30, v189
	v_cmp_gt_u32_e64 s[66:67], s76, v190
	s_nop 1
	v_cndmask_b32_e64 v190, v119, v223, s[66:67]
	v_cndmask_b32_e64 v119, v119, v190, s[14:15]
	v_subrev_u32_e32 v190, 17, v189
	v_cmp_lt_u32_e64 s[70:71], s68, v190
	v_max3_f32 v188, v188, v118, v119
	s_nop 0
	v_cndmask_b32_e64 v190, v223, v112, s[70:71]
	v_cndmask_b32_e64 v112, v112, v190, s[14:15]
	v_add_u32_e32 v190, -16, v189
	v_cmp_lt_u32_e64 s[70:71], s68, v190
	s_nop 1
	v_cndmask_b32_e64 v190, v223, v113, s[70:71]
	v_cndmask_b32_e64 v113, v113, v190, s[14:15]
	v_add_u32_e32 v190, -15, v189
	v_cmp_lt_u32_e64 s[70:71], s68, v190
	v_max3_f32 v188, v188, v112, v113
	s_nop 0
	v_cndmask_b32_e64 v190, v223, v114, s[70:71]
	v_cndmask_b32_e64 v191, v114, v190, s[14:15]
	v_add_u32_e32 v114, -14, v189
	v_cmp_lt_u32_e64 s[70:71], s68, v114
	s_nop 1
	v_cndmask_b32_e64 v114, v223, v115, s[70:71]
	v_cndmask_b32_e64 v115, v115, v114, s[14:15]
	v_max3_f32 v114, v188, v191, v115
	ds_bpermute_b32 v188, v161, v114
	s_waitcnt lgkmcnt(0)
	v_max_f32_e32 v188, v188, v188
	v_max_f32_e32 v114, v114, v188
	ds_bpermute_b32 v188, v221, v114
	s_waitcnt lgkmcnt(0)
	v_max3_f32 v224, v186, v114, v188
	v_sub_f32_e32 v114, v186, v224
	v_mul_f32_e32 v195, 0xbe38aa3b, v224
	v_mul_f32_e32 v193, 0x3e38aa3b, v114
	v_fmamk_f32 v114, v128, 0x3e38aa3b, v195
	v_exp_f32_e32 v218, v114
	v_fmamk_f32 v114, v129, 0x3e38aa3b, v195
	v_exp_f32_e32 v216, v114
	v_fmamk_f32 v114, v130, 0x3e38aa3b, v195
	v_exp_f32_e32 v214, v114
	v_fmamk_f32 v114, v131, 0x3e38aa3b, v195
	v_exp_f32_e32 v212, v114
	v_fmamk_f32 v114, v140, 0x3e38aa3b, v195
	v_exp_f32_e32 v210, v114
	v_fmamk_f32 v114, v141, 0x3e38aa3b, v195
	v_exp_f32_e32 v208, v114
	v_fmamk_f32 v114, v142, 0x3e38aa3b, v195
	v_exp_f32_e32 v206, v114
	v_fmamk_f32 v114, v143, 0x3e38aa3b, v195
	v_exp_f32_e32 v204, v114
	v_fmamk_f32 v114, v136, 0x3e38aa3b, v195
	v_exp_f32_e32 v202, v114
	v_fmamk_f32 v114, v137, 0x3e38aa3b, v195
	v_exp_f32_e32 v200, v114
	v_fmamk_f32 v114, v138, 0x3e38aa3b, v195
	v_exp_f32_e32 v198, v114
	v_fmamk_f32 v114, v139, 0x3e38aa3b, v195
	v_exp_f32_e32 v196, v114
	v_fmamk_f32 v114, v132, 0x3e38aa3b, v195
	v_exp_f32_e32 v194, v114
	v_fmamk_f32 v114, v133, 0x3e38aa3b, v195
	v_exp_f32_e32 v192, v114
	v_fmamk_f32 v114, v134, 0x3e38aa3b, v195
	v_exp_f32_e32 v190, v114
	v_fmamk_f32 v114, v135, 0x3e38aa3b, v195
	v_exp_f32_e32 v188, v114
	v_fmamk_f32 v114, v124, 0x3e38aa3b, v195
	v_exp_f32_e32 v186, v114
	v_fmamk_f32 v114, v125, 0x3e38aa3b, v195
	v_exp_f32_e32 v142, v114
	v_fmamk_f32 v114, v126, 0x3e38aa3b, v195
	v_exp_f32_e32 v140, v114
	v_fmamk_f32 v114, v127, 0x3e38aa3b, v195
	v_exp_f32_e32 v138, v114
	v_fmamk_f32 v114, v120, 0x3e38aa3b, v195
	v_exp_f32_e32 v136, v114
	v_fmamk_f32 v114, v121, 0x3e38aa3b, v195
	v_exp_f32_e32 v134, v114
	v_fmamk_f32 v114, v122, 0x3e38aa3b, v195
	v_exp_f32_e32 v132, v114
	v_fmamk_f32 v114, v123, 0x3e38aa3b, v195
	v_exp_f32_e32 v130, v114
	v_fmamk_f32 v114, v116, 0x3e38aa3b, v195
	v_exp_f32_e32 v128, v114
	v_fmamk_f32 v114, v117, 0x3e38aa3b, v195
	v_exp_f32_e32 v126, v114
	v_fmamk_f32 v114, v118, 0x3e38aa3b, v195
	v_fmamk_f32 v112, v112, 0x3e38aa3b, v195
	v_exp_f32_e32 v122, v114
	v_fmamk_f32 v114, v119, 0x3e38aa3b, v195
	v_exp_f32_e32 v116, v112
	v_fmamk_f32 v112, v113, 0x3e38aa3b, v195
	v_exp_f32_e32 v118, v114
	v_exp_f32_e32 v114, v112
	v_exp_f32_e32 v112, v193
	v_fmamk_f32 v113, v191, 0x3e38aa3b, v195
	v_exp_f32_e32 v124, v113
	v_fmac_f32_e32 v195, 0x3e38aa3b, v115
	v_pk_mul_f32 v[78:79], v[78:79], v[112:113] op_sel_hi:[1,0]
	v_pk_mul_f32 v[76:77], v[76:77], v[112:113] op_sel_hi:[1,0]
	v_pk_mul_f32 v[74:75], v[74:75], v[112:113] op_sel_hi:[1,0]
	v_pk_mul_f32 v[72:73], v[72:73], v[112:113] op_sel_hi:[1,0]
	v_pk_mul_f32 v[58:59], v[58:59], v[112:113] op_sel_hi:[1,0]
	v_pk_mul_f32 v[56:57], v[56:57], v[112:113] op_sel_hi:[1,0]
	v_pk_mul_f32 v[34:35], v[34:35], v[112:113] op_sel_hi:[1,0]
	v_pk_mul_f32 v[32:33], v[32:33], v[112:113] op_sel_hi:[1,0]
	v_add_u32_e32 v113, 0xffffff6f, v189
	v_cmp_lt_u32_e64 s[70:71], s68, v113
	v_add_u32_e32 v115, 0xffffff71, v189
	v_exp_f32_e32 v120, v195
	v_cndmask_b32_e64 v113, v223, v80, s[70:71]
	v_cndmask_b32_e32 v80, v80, v113, vcc
	v_add_u32_e32 v113, 0xffffff70, v189
	v_cmp_lt_u32_e64 s[70:71], s68, v113
	s_nop 1
	v_cndmask_b32_e64 v113, v223, v81, s[70:71]
	v_cmp_lt_u32_e64 s[70:71], s68, v115
	v_cndmask_b32_e32 v113, v81, v113, vcc
	v_max3_f32 v81, v80, s77, v113
	v_cndmask_b32_e64 v115, v223, v82, s[70:71]
	v_cndmask_b32_e32 v115, v82, v115, vcc
	v_add_u32_e32 v82, 0xffffff72, v189
	v_cmp_lt_u32_e64 s[70:71], s68, v82
	s_nop 1
	v_cndmask_b32_e64 v82, v223, v83, s[70:71]
	v_cndmask_b32_e32 v117, v83, v82, vcc
	v_cndmask_b32_e64 v82, v96, v223, s[6:7]
	v_cndmask_b32_e32 v96, v96, v82, vcc
	v_cndmask_b32_e64 v82, v97, v223, s[10:11]
	v_cndmask_b32_e32 v97, v97, v82, vcc
	v_cndmask_b32_e64 v82, v98, v223, s[12:13]
	v_cndmask_b32_e32 v98, v98, v82, vcc
	v_cndmask_b32_e64 v82, v99, v223, s[16:17]
	v_cndmask_b32_e32 v99, v99, v82, vcc
	v_cndmask_b32_e64 v82, v104, v223, s[18:19]
	v_cndmask_b32_e32 v104, v104, v82, vcc
	v_cndmask_b32_e64 v82, v105, v223, s[20:21]
	v_cndmask_b32_e32 v105, v105, v82, vcc
	v_cndmask_b32_e64 v82, v106, v223, s[22:23]
	v_cndmask_b32_e32 v106, v106, v82, vcc
	v_cndmask_b32_e64 v82, v107, v223, s[24:25]
	v_cndmask_b32_e32 v107, v107, v82, vcc
	v_cndmask_b32_e64 v82, v108, v223, s[26:27]
	v_cndmask_b32_e32 v108, v108, v82, vcc
	v_cndmask_b32_e64 v82, v109, v223, s[28:29]
	v_cndmask_b32_e32 v109, v109, v82, vcc
	v_cndmask_b32_e64 v82, v110, v223, s[30:31]
	v_cndmask_b32_e32 v110, v110, v82, vcc
	v_cndmask_b32_e64 v82, v111, v223, s[34:35]
	v_cndmask_b32_e32 v111, v111, v82, vcc
	v_cndmask_b32_e64 v82, v84, v223, s[36:37]
	v_cndmask_b32_e64 v119, v84, v82, s[14:15]
	v_cndmask_b32_e64 v82, v85, v223, s[38:39]
	v_cndmask_b32_e64 v121, v85, v82, s[14:15]
	v_cndmask_b32_e64 v82, v86, v223, s[40:41]
	v_max3_f32 v81, v81, v115, v117
	v_cndmask_b32_e64 v123, v86, v82, s[14:15]
	v_cndmask_b32_e64 v82, v87, v223, s[42:43]
	v_max3_f32 v81, v81, v96, v97
	v_cndmask_b32_e64 v125, v87, v82, s[14:15]
	v_cndmask_b32_e64 v82, v88, v223, s[44:45]
	v_max3_f32 v81, v81, v98, v99
	v_cndmask_b32_e64 v127, v88, v82, s[14:15]
	v_cndmask_b32_e64 v82, v89, v223, s[46:47]
	v_max3_f32 v81, v81, v104, v105
	v_cndmask_b32_e64 v129, v89, v82, s[14:15]
	v_cndmask_b32_e64 v82, v90, v223, s[48:49]
	v_max3_f32 v81, v81, v106, v107
	v_cndmask_b32_e64 v90, v90, v82, s[14:15]
	v_cndmask_b32_e64 v82, v91, v223, s[50:51]
	v_max3_f32 v81, v81, v108, v109
	v_cndmask_b32_e64 v91, v91, v82, s[14:15]
	v_cndmask_b32_e64 v82, v92, v223, s[52:53]
	v_max3_f32 v81, v81, v110, v111
	v_cndmask_b32_e64 v92, v92, v82, s[14:15]
	v_cndmask_b32_e64 v82, v93, v223, s[54:55]
	v_max3_f32 v81, v81, v119, v121
	v_cndmask_b32_e64 v93, v93, v82, s[14:15]
	v_cndmask_b32_e64 v82, v94, v223, s[56:57]
	v_max3_f32 v81, v81, v123, v125
	v_cndmask_b32_e64 v94, v94, v82, s[14:15]
	v_cndmask_b32_e64 v82, v95, v223, s[58:59]
	v_max3_f32 v81, v81, v127, v129
	v_cndmask_b32_e64 v95, v95, v82, s[14:15]
	v_cndmask_b32_e64 v82, v100, v223, s[60:61]
	v_max3_f32 v81, v81, v90, v91
	v_cndmask_b32_e64 v100, v100, v82, s[14:15]
	v_cndmask_b32_e64 v82, v101, v223, s[62:63]
	v_max3_f32 v81, v81, v92, v93
	v_cndmask_b32_e64 v101, v101, v82, s[14:15]
	v_cndmask_b32_e64 v82, v102, v223, s[64:65]
	v_max3_f32 v81, v81, v94, v95
	v_cndmask_b32_e64 v102, v102, v82, s[14:15]
	v_cndmask_b32_e64 v82, v103, v223, s[66:67]
	v_max3_f32 v81, v81, v100, v101
	v_cndmask_b32_e64 v103, v103, v82, s[14:15]
	s_branch .Lattnb_join
.Lattnb_fast:
	s_cmp_lt_i32 s4, s33
	s_cselect_b64 s[12:13], -1, 0
	s_and_b64 vcc, s[86:87], s[12:13]
	s_cmp_lt_i32 s10, s33
	s_cselect_b64 s[14:15], -1, 0
	s_and_b64 s[14:15], s[86:87], s[14:15]
	v_max3_f32 v188, v128, s77, v129
	v_max3_f32 v188, v188, v130, v131
	v_max3_f32 v188, v188, v140, v141
	v_max3_f32 v188, v188, v142, v143
	v_max3_f32 v188, v188, v136, v137
	v_max3_f32 v188, v188, v138, v139
	v_max3_f32 v188, v188, v132, v133
	v_max3_f32 v188, v188, v134, v135
	v_max3_f32 v188, v188, v124, v125
	v_max3_f32 v188, v188, v126, v127
	v_max3_f32 v188, v188, v120, v121
	v_max3_f32 v188, v188, v122, v123
	v_max3_f32 v188, v188, v116, v117
	v_max3_f32 v188, v188, v118, v119
	v_max3_f32 v188, v188, v112, v113
	v_mov_b32_e32 v191, v114
	v_max3_f32 v114, v188, v191, v115
	ds_bpermute_b32 v188, v161, v114
	s_waitcnt lgkmcnt(0)
	v_max_f32_e32 v188, v188, v188
	v_max_f32_e32 v114, v114, v188
	ds_bpermute_b32 v188, v221, v114
	s_waitcnt lgkmcnt(0)
	v_max3_f32 v224, v186, v114, v188
	v_sub_f32_e32 v114, v186, v224
	v_mul_f32_e32 v195, 0xbe38aa3b, v224
	v_mul_f32_e32 v193, 0x3e38aa3b, v114
	v_fmamk_f32 v114, v128, 0x3e38aa3b, v195
	v_exp_f32_e32 v218, v114
	v_fmamk_f32 v114, v129, 0x3e38aa3b, v195
	v_exp_f32_e32 v216, v114
	v_fmamk_f32 v114, v130, 0x3e38aa3b, v195
	v_exp_f32_e32 v214, v114
	v_fmamk_f32 v114, v131, 0x3e38aa3b, v195
	v_exp_f32_e32 v212, v114
	v_fmamk_f32 v114, v140, 0x3e38aa3b, v195
	v_exp_f32_e32 v210, v114
	v_fmamk_f32 v114, v141, 0x3e38aa3b, v195
	v_exp_f32_e32 v208, v114
	v_fmamk_f32 v114, v142, 0x3e38aa3b, v195
	v_exp_f32_e32 v206, v114
	v_fmamk_f32 v114, v143, 0x3e38aa3b, v195
	v_exp_f32_e32 v204, v114
	v_fmamk_f32 v114, v136, 0x3e38aa3b, v195
	v_exp_f32_e32 v202, v114
	v_fmamk_f32 v114, v137, 0x3e38aa3b, v195
	v_exp_f32_e32 v200, v114
	v_fmamk_f32 v114, v138, 0x3e38aa3b, v195
	v_exp_f32_e32 v198, v114
	v_fmamk_f32 v114, v139, 0x3e38aa3b, v195
	v_exp_f32_e32 v196, v114
	v_fmamk_f32 v114, v132, 0x3e38aa3b, v195
	v_exp_f32_e32 v194, v114
	v_fmamk_f32 v114, v133, 0x3e38aa3b, v195
	v_exp_f32_e32 v192, v114
	v_fmamk_f32 v114, v134, 0x3e38aa3b, v195
	v_exp_f32_e32 v190, v114
	v_fmamk_f32 v114, v135, 0x3e38aa3b, v195
	v_exp_f32_e32 v188, v114
	v_fmamk_f32 v114, v124, 0x3e38aa3b, v195
	v_exp_f32_e32 v186, v114
	v_fmamk_f32 v114, v125, 0x3e38aa3b, v195
	v_exp_f32_e32 v142, v114
	v_fmamk_f32 v114, v126, 0x3e38aa3b, v195
	v_exp_f32_e32 v140, v114
	v_fmamk_f32 v114, v127, 0x3e38aa3b, v195
	v_exp_f32_e32 v138, v114
	v_fmamk_f32 v114, v120, 0x3e38aa3b, v195
	v_exp_f32_e32 v136, v114
	v_fmamk_f32 v114, v121, 0x3e38aa3b, v195
	v_exp_f32_e32 v134, v114
	v_fmamk_f32 v114, v122, 0x3e38aa3b, v195
	v_exp_f32_e32 v132, v114
	v_fmamk_f32 v114, v123, 0x3e38aa3b, v195
	v_exp_f32_e32 v130, v114
	v_fmamk_f32 v114, v116, 0x3e38aa3b, v195
	v_exp_f32_e32 v128, v114
	v_fmamk_f32 v114, v117, 0x3e38aa3b, v195
	v_exp_f32_e32 v126, v114
	v_fmamk_f32 v114, v118, 0x3e38aa3b, v195
	v_fmamk_f32 v112, v112, 0x3e38aa3b, v195
	v_exp_f32_e32 v122, v114
	v_fmamk_f32 v114, v119, 0x3e38aa3b, v195
	v_exp_f32_e32 v116, v112
	v_fmamk_f32 v112, v113, 0x3e38aa3b, v195
	v_exp_f32_e32 v118, v114
	v_exp_f32_e32 v114, v112
	v_exp_f32_e32 v112, v193
	v_fmamk_f32 v113, v191, 0x3e38aa3b, v195
	v_exp_f32_e32 v124, v113
	v_fmac_f32_e32 v195, 0x3e38aa3b, v115
	v_pk_mul_f32 v[78:79], v[78:79], v[112:113] op_sel_hi:[1,0]
	v_pk_mul_f32 v[76:77], v[76:77], v[112:113] op_sel_hi:[1,0]
	v_pk_mul_f32 v[74:75], v[74:75], v[112:113] op_sel_hi:[1,0]
	v_pk_mul_f32 v[72:73], v[72:73], v[112:113] op_sel_hi:[1,0]
	v_pk_mul_f32 v[58:59], v[58:59], v[112:113] op_sel_hi:[1,0]
	v_pk_mul_f32 v[56:57], v[56:57], v[112:113] op_sel_hi:[1,0]
	v_pk_mul_f32 v[34:35], v[34:35], v[112:113] op_sel_hi:[1,0]
	v_pk_mul_f32 v[32:33], v[32:33], v[112:113] op_sel_hi:[1,0]
	v_exp_f32_e32 v120, v195
	v_mov_b32_e32 v113, v81
	v_max3_f32 v81, v80, s77, v113
	v_mov_b32_e32 v115, v82
	v_mov_b32_e32 v117, v83
	v_mov_b32_e32 v119, v84
	v_mov_b32_e32 v121, v85
	v_max3_f32 v81, v81, v115, v117
	v_mov_b32_e32 v123, v86
	v_max3_f32 v81, v81, v96, v97
	v_mov_b32_e32 v125, v87
	v_max3_f32 v81, v81, v98, v99
	v_mov_b32_e32 v127, v88
	v_max3_f32 v81, v81, v104, v105
	v_mov_b32_e32 v129, v89
	v_max3_f32 v81, v81, v106, v107
	v_max3_f32 v81, v81, v108, v109
	v_max3_f32 v81, v81, v110, v111
	v_max3_f32 v81, v81, v119, v121
	v_max3_f32 v81, v81, v123, v125
	v_max3_f32 v81, v81, v127, v129
	v_max3_f32 v81, v81, v90, v91
	v_max3_f32 v81, v81, v92, v93
	v_max3_f32 v81, v81, v94, v95
	v_max3_f32 v81, v81, v100, v101
.Lattnb_join:
	v_max3_f32 v81, v81, v102, v103
	ds_bpermute_b32 v86, v161, v81
	v_cvt_pk_bf16_f32 v82, v218, v216
	v_cvt_pk_bf16_f32 v83, v214, v212
	v_cvt_pk_bf16_f32 v84, v210, v208
	v_cvt_pk_bf16_f32 v85, v206, v204
	s_waitcnt lgkmcnt(0)
	v_max_f32_e32 v86, v86, v86
	v_max_f32_e32 v81, v81, v86
	ds_bpermute_b32 v131, v221, v81
	v_cvt_pk_bf16_f32 v86, v202, v200
	v_cvt_pk_bf16_f32 v87, v198, v196
	v_cvt_pk_bf16_f32 v88, v194, v192
	v_cvt_pk_bf16_f32 v89, v190, v188
	s_waitcnt lgkmcnt(0)
	v_max3_f32 v81, v187, v81, v131
	v_mul_f32_e32 v226, 0xbe38aa3b, v81
	v_fmamk_f32 v80, v80, 0x3e38aa3b, v226
	v_exp_f32_e32 v219, v80
	v_fmamk_f32 v80, v113, 0x3e38aa3b, v226
	v_exp_f32_e32 v217, v80
	v_fmamk_f32 v80, v115, 0x3e38aa3b, v226
	v_exp_f32_e32 v215, v80
	v_fmamk_f32 v80, v117, 0x3e38aa3b, v226
	v_exp_f32_e32 v213, v80
	v_fmamk_f32 v80, v96, 0x3e38aa3b, v226
	v_exp_f32_e32 v211, v80
	v_fmamk_f32 v80, v97, 0x3e38aa3b, v226
	v_exp_f32_e32 v209, v80
	v_fmamk_f32 v80, v98, 0x3e38aa3b, v226
	v_exp_f32_e32 v207, v80
	v_fmamk_f32 v80, v99, 0x3e38aa3b, v226
	v_exp_f32_e32 v205, v80
	v_fmamk_f32 v80, v104, 0x3e38aa3b, v226
	v_exp_f32_e32 v203, v80
	v_fmamk_f32 v80, v105, 0x3e38aa3b, v226
	v_exp_f32_e32 v201, v80
	v_fmamk_f32 v80, v106, 0x3e38aa3b, v226
	v_exp_f32_e32 v199, v80
	v_fmamk_f32 v80, v107, 0x3e38aa3b, v226
	v_exp_f32_e32 v197, v80
	v_fmamk_f32 v80, v108, 0x3e38aa3b, v226
	v_exp_f32_e32 v195, v80
	v_fmamk_f32 v80, v109, 0x3e38aa3b, v226
	v_exp_f32_e32 v193, v80
	v_fmamk_f32 v80, v110, 0x3e38aa3b, v226
	v_exp_f32_e32 v191, v80
	v_fmamk_f32 v80, v111, 0x3e38aa3b, v226
	v_exp_f32_e32 v189, v80
	v_fmamk_f32 v80, v119, 0x3e38aa3b, v226
	v_sub_f32_e32 v131, v187, v81
	v_exp_f32_e32 v187, v80
	v_fmamk_f32 v80, v121, 0x3e38aa3b, v226
	v_exp_f32_e32 v143, v80
	v_fmamk_f32 v80, v123, 0x3e38aa3b, v226
	v_exp_f32_e32 v141, v80
	v_fmamk_f32 v80, v125, 0x3e38aa3b, v226
	v_exp_f32_e32 v139, v80
	v_fmamk_f32 v80, v127, 0x3e38aa3b, v226
	v_exp_f32_e32 v137, v80
	v_fmamk_f32 v80, v129, 0x3e38aa3b, v226
	v_exp_f32_e32 v135, v80
	v_fmamk_f32 v80, v90, 0x3e38aa3b, v226
	v_exp_f32_e32 v133, v80
	v_fmamk_f32 v80, v91, 0x3e38aa3b, v226
	v_mul_f32_e32 v225, 0x3e38aa3b, v131
	v_exp_f32_e32 v131, v80
	v_fmamk_f32 v80, v92, 0x3e38aa3b, v226
	v_exp_f32_e32 v129, v80
	v_fmamk_f32 v80, v93, 0x3e38aa3b, v226
	v_exp_f32_e32 v127, v80
	v_fmamk_f32 v80, v94, 0x3e38aa3b, v226
	v_exp_f32_e32 v123, v80
	v_fmamk_f32 v80, v95, 0x3e38aa3b, v226
	v_exp_f32_e32 v119, v80
	v_fmamk_f32 v80, v100, 0x3e38aa3b, v226
	v_exp_f32_e32 v117, v80
	v_fmamk_f32 v80, v101, 0x3e38aa3b, v226
	v_exp_f32_e32 v115, v80
	v_fmamk_f32 v90, v102, 0x3e38aa3b, v226
	v_exp_f32_e32 v80, v225
	v_fmac_f32_e32 v226, 0x3e38aa3b, v103
	v_exp_f32_e32 v125, v90
	v_exp_f32_e32 v121, v226
	v_pk_mul_f32 v[14:15], v[14:15], v[80:81] op_sel_hi:[1,0]
	v_pk_mul_f32 v[12:13], v[12:13], v[80:81] op_sel_hi:[1,0]
	v_pk_mul_f32 v[10:11], v[10:11], v[80:81] op_sel_hi:[1,0]
	v_pk_mul_f32 v[8:9], v[8:9], v[80:81] op_sel_hi:[1,0]
	v_pk_mul_f32 v[6:7], v[6:7], v[80:81] op_sel_hi:[1,0]
	v_pk_mul_f32 v[4:5], v[4:5], v[80:81] op_sel_hi:[1,0]
	v_pk_mul_f32 v[2:3], v[2:3], v[80:81] op_sel_hi:[1,0]
	v_pk_mul_f32 v[0:1], v[0:1], v[80:81] op_sel_hi:[1,0]
	v_cvt_pk_bf16_f32 v90, v219, v217
	v_cvt_pk_bf16_f32 v91, v215, v213
	v_cvt_pk_bf16_f32 v92, v211, v209
	v_cvt_pk_bf16_f32 v93, v207, v205
	v_cvt_pk_bf16_f32 v94, v203, v201
	v_cvt_pk_bf16_f32 v95, v199, v197
	v_cvt_pk_bf16_f32 v96, v195, v193
	v_cvt_pk_bf16_f32 v97, v191, v189
	s_setprio 1
	ds_read_b128 v[98:101], v222 offset:10240
	ds_read_b128 v[102:105], v222 offset:10304
	s_andn2_b64 vcc, exec, s[92:93]
	s_waitcnt lgkmcnt(1)
	v_mfma_f32_16x16x32_bf16 v[76:79], v[98:101], v[82:85], v[76:79]
	v_mfma_f32_16x16x32_bf16 v[12:15], v[98:101], v[90:93], v[12:15]
	s_waitcnt lgkmcnt(0)
	v_mfma_f32_16x16x32_bf16 v[76:79], v[102:105], v[86:89], v[76:79]
	v_mfma_f32_16x16x32_bf16 v[12:15], v[102:105], v[94:97], v[12:15]
	ds_read_b128 v[98:101], v222 offset:12800
	ds_read_b128 v[102:105], v222 offset:12864
	s_waitcnt lgkmcnt(1)
	v_mfma_f32_16x16x32_bf16 v[72:75], v[98:101], v[82:85], v[72:75]
	v_mfma_f32_16x16x32_bf16 v[8:11], v[98:101], v[90:93], v[8:11]
	s_waitcnt lgkmcnt(0)
	v_mfma_f32_16x16x32_bf16 v[72:75], v[102:105], v[86:89], v[72:75]
	v_mfma_f32_16x16x32_bf16 v[8:11], v[102:105], v[94:97], v[8:11]
	ds_read_b128 v[98:101], v222 offset:15360
	ds_read_b128 v[102:105], v222 offset:15424
	s_waitcnt lgkmcnt(1)
	v_mfma_f32_16x16x32_bf16 v[56:59], v[98:101], v[82:85], v[56:59]
	v_mfma_f32_16x16x32_bf16 v[4:7], v[98:101], v[90:93], v[4:7]
	s_waitcnt lgkmcnt(0)
	v_mfma_f32_16x16x32_bf16 v[56:59], v[102:105], v[86:89], v[56:59]
	v_mfma_f32_16x16x32_bf16 v[4:7], v[102:105], v[94:97], v[4:7]
	ds_read_b128 v[98:101], v222 offset:17920
	ds_read_b128 v[102:105], v222 offset:17984
	s_waitcnt lgkmcnt(1)
	v_mfma_f32_16x16x32_bf16 v[32:35], v[98:101], v[82:85], v[32:35]
	v_mfma_f32_16x16x32_bf16 v[0:3], v[98:101], v[90:93], v[0:3]
	s_waitcnt lgkmcnt(0)
	v_mfma_f32_16x16x32_bf16 v[32:35], v[102:105], v[86:89], v[32:35]
	v_mfma_f32_16x16x32_bf16 v[0:3], v[102:105], v[94:97], v[0:3]
	s_cbranch_vccnz .LBB0_1272
	ds_read_b128 v[82:85], v222 offset:30720
	ds_read_b128 v[98:101], v222 offset:30784
	v_cvt_pk_bf16_f32 v90, v186, v142
	v_cvt_pk_bf16_f32 v91, v140, v138
	v_cvt_pk_bf16_f32 v92, v136, v134
	v_cvt_pk_bf16_f32 v93, v132, v130
	v_cvt_pk_bf16_f32 v94, v187, v143
	v_cvt_pk_bf16_f32 v95, v141, v139
	v_cvt_pk_bf16_f32 v96, v137, v135
	v_cvt_pk_bf16_f32 v97, v133, v131
	s_waitcnt lgkmcnt(1)
	v_mfma_f32_16x16x32_bf16 v[76:79], v[82:85], v[90:93], v[76:79]
	v_cvt_pk_bf16_f32 v86, v128, v126
	v_cvt_pk_bf16_f32 v87, v122, v118
	v_cvt_pk_bf16_f32 v88, v116, v114
	v_mfma_f32_16x16x32_bf16 v[12:15], v[82:85], v[94:97], v[12:15]
	v_cvt_pk_bf16_f32 v89, v124, v120
	v_cvt_pk_bf16_f32 v82, v129, v127
	v_cvt_pk_bf16_f32 v83, v123, v119
	v_cvt_pk_bf16_f32 v84, v117, v115
	v_cvt_pk_bf16_f32 v85, v125, v121
	s_waitcnt lgkmcnt(0)
	v_mfma_f32_16x16x32_bf16 v[76:79], v[98:101], v[86:89], v[76:79]
	v_mfma_f32_16x16x32_bf16 v[12:15], v[98:101], v[82:85], v[12:15]
	ds_read_b128 v[98:101], v222 offset:33280
	ds_read_b128 v[102:105], v222 offset:33344
	s_waitcnt lgkmcnt(1)
	v_mfma_f32_16x16x32_bf16 v[72:75], v[98:101], v[90:93], v[72:75]
	v_mfma_f32_16x16x32_bf16 v[8:11], v[98:101], v[94:97], v[8:11]
	s_waitcnt lgkmcnt(0)
	v_mfma_f32_16x16x32_bf16 v[72:75], v[102:105], v[86:89], v[72:75]
	v_mfma_f32_16x16x32_bf16 v[8:11], v[102:105], v[82:85], v[8:11]
	ds_read_b128 v[98:101], v222 offset:35840
	ds_read_b128 v[102:105], v222 offset:35904
	s_waitcnt lgkmcnt(1)
	v_mfma_f32_16x16x32_bf16 v[56:59], v[98:101], v[90:93], v[56:59]
	v_mfma_f32_16x16x32_bf16 v[4:7], v[98:101], v[94:97], v[4:7]
	s_waitcnt lgkmcnt(0)
	v_mfma_f32_16x16x32_bf16 v[56:59], v[102:105], v[86:89], v[56:59]
	v_mfma_f32_16x16x32_bf16 v[4:7], v[102:105], v[82:85], v[4:7]
	ds_read_b128 v[98:101], v222 offset:38400
	ds_read_b128 v[102:105], v222 offset:38464
	s_waitcnt lgkmcnt(1)
	v_mfma_f32_16x16x32_bf16 v[32:35], v[98:101], v[90:93], v[32:35]
	v_mfma_f32_16x16x32_bf16 v[0:3], v[98:101], v[94:97], v[0:3]
	s_waitcnt lgkmcnt(0)
	v_mfma_f32_16x16x32_bf16 v[32:35], v[102:105], v[86:89], v[32:35]
	v_mfma_f32_16x16x32_bf16 v[0:3], v[102:105], v[82:85], v[0:3]

	.amdhsa_kernel _Z11mega_kernel6Params
		.amdhsa_group_segment_fixed_size 77840
		.amdhsa_private_segment_fixed_size 0
		.amdhsa_kernarg_size 616
		.amdhsa_user_sgpr_count 2
		.amdhsa_user_sgpr_dispatch_ptr 0
		.amdhsa_user_sgpr_queue_ptr 0
		.amdhsa_user_sgpr_kernarg_segment_ptr 1
		.amdhsa_user_sgpr_dispatch_id 0
		.amdhsa_user_sgpr_kernarg_preload_length 0
		.amdhsa_user_sgpr_kernarg_preload_offset 0
		.amdhsa_user_sgpr_private_segment_size 0
		.amdhsa_uses_dynamic_stack 0
		.amdhsa_enable_private_segment 0
		.amdhsa_system_sgpr_workgroup_id_x 1
		.amdhsa_system_sgpr_workgroup_id_y 0
		.amdhsa_system_sgpr_workgroup_id_z 0
		.amdhsa_system_sgpr_workgroup_info 0
		.amdhsa_system_vgpr_workitem_id 2
		.amdhsa_next_free_vgpr 254
		.amdhsa_next_free_sgpr 102
		.amdhsa_accum_offset 256
		.amdhsa_reserve_vcc 1
		.amdhsa_float_round_mode_32 0
		.amdhsa_float_round_mode_16_64 0
		.amdhsa_float_denorm_mode_32 3
		.amdhsa_float_denorm_mode_16_64 3
		.amdhsa_dx10_clamp 1
		.amdhsa_ieee_mode 1
		.amdhsa_fp16_overflow 0
		.amdhsa_tg_split 0
		.amdhsa_exception_fp_ieee_invalid_op 0
		.amdhsa_exception_fp_denorm_src 0
		.amdhsa_exception_fp_ieee_div_zero 0
		.amdhsa_exception_fp_ieee_overflow 0
		.amdhsa_exception_fp_ieee_underflow 0
		.amdhsa_exception_fp_ieee_inexact 0
		.amdhsa_exception_int_div_zero 0
	.end_amdhsa_kernel

amdhsa.kernels:
  - .agpr_count:     0
    .args:
      - .offset:         0
        .size:           360
        .value_kind:     by_value
      - .offset:         360
        .size:           4
        .value_kind:     hidden_block_count_x
      - .offset:         364
        .size:           4
        .value_kind:     hidden_block_count_y
      - .offset:         368
        .size:           4
        .value_kind:     hidden_block_count_z
      - .offset:         372
        .size:           2
        .value_kind:     hidden_group_size_x
      - .offset:         374
        .size:           2
        .value_kind:     hidden_group_size_y
      - .offset:         376
        .size:           2
        .value_kind:     hidden_group_size_z
      - .offset:         378
        .size:           2
        .value_kind:     hidden_remainder_x
      - .offset:         380
        .size:           2
        .value_kind:     hidden_remainder_y
      - .offset:         382
        .size:           2
        .value_kind:     hidden_remainder_z
      - .offset:         400
        .size:           8
        .value_kind:     hidden_global_offset_x
      - .offset:         408
        .size:           8
        .value_kind:     hidden_global_offset_y
      - .offset:         416
        .size:           8
        .value_kind:     hidden_global_offset_z
      - .offset:         424
        .size:           2
        .value_kind:     hidden_grid_dims
      - .offset:         448
        .size:           8
        .value_kind:     hidden_multigrid_sync_arg
    .group_segment_fixed_size: 77840
    .kernarg_segment_align: 8
    .kernarg_segment_size: 616
    .language:       OpenCL C
    .language_version:
      - 2
      - 0
    .max_flat_workgroup_size: 256
    .name:           _Z11mega_kernel6Params
    .private_segment_fixed_size: 0
    .sgpr_count:     108
    .sgpr_spill_count: 29
    .symbol:         _Z11mega_kernel6Params.kd
    .uniform_work_group_size: 1
    .uses_dynamic_stack: false
    .vgpr_count:     254
    .vgpr_spill_count: 0
    .wavefront_size: 64
